# resid epilogue X stores marked sc0 sc1 (write-through, lighter L2 writeback at the barrier); new rotation code form
# speedup vs baseline: 1.0110x; 1.0057x over previous
.Lr6_loop:
	s_waitcnt vmcnt(8)
	s_barrier
	ds_read_b128 v[64:67], v252 offset:0
	ds_read_b128 v[96:99], v254 offset:32768
	ds_read_b128 v[100:103], v254 offset:34816
	ds_read_b128 v[104:107], v254 offset:36864
	ds_read_b128 v[108:111], v254 offset:38912
	ds_read_b128 v[68:71], v252 offset:2048
	ds_read_b128 v[72:75], v252 offset:4096
	ds_read_b128 v[76:79], v252 offset:6144
	v_mfma_f32_16x16x32_bf16 v[0:3], v[80:83], v[112:115], v[0:3]
	v_mfma_f32_16x16x32_bf16 v[4:7], v[80:83], v[116:119], v[4:7]
	v_mfma_f32_16x16x32_bf16 v[8:11], v[80:83], v[120:123], v[8:11]
	v_mfma_f32_16x16x32_bf16 v[12:15], v[80:83], v[124:127], v[12:15]
	v_mfma_f32_16x16x32_bf16 v[16:19], v[84:87], v[112:115], v[16:19]
	v_mfma_f32_16x16x32_bf16 v[20:23], v[84:87], v[116:119], v[20:23]
	v_mfma_f32_16x16x32_bf16 v[24:27], v[84:87], v[120:123], v[24:27]
	v_mfma_f32_16x16x32_bf16 v[28:31], v[84:87], v[124:127], v[28:31]
	v_mfma_f32_16x16x32_bf16 v[32:35], v[88:91], v[112:115], v[32:35]
	v_mfma_f32_16x16x32_bf16 v[36:39], v[88:91], v[116:119], v[36:39]
	v_mfma_f32_16x16x32_bf16 v[40:43], v[88:91], v[120:123], v[40:43]
	v_mfma_f32_16x16x32_bf16 v[44:47], v[88:91], v[124:127], v[44:47]
	v_mfma_f32_16x16x32_bf16 v[48:51], v[92:95], v[112:115], v[48:51]
	v_mfma_f32_16x16x32_bf16 v[52:55], v[92:95], v[116:119], v[52:55]
	v_mfma_f32_16x16x32_bf16 v[56:59], v[92:95], v[120:123], v[56:59]
	v_mfma_f32_16x16x32_bf16 v[60:63], v[92:95], v[124:127], v[60:63]
	ds_read_b128 v[80:83], v253 offset:0
	ds_read_b128 v[112:115], v255 offset:32768
	ds_read_b128 v[116:119], v255 offset:34816
	ds_read_b128 v[120:123], v255 offset:36864
	ds_read_b128 v[124:127], v255 offset:38912
	ds_read_b128 v[84:87], v253 offset:2048
	ds_read_b128 v[88:91], v253 offset:4096
	ds_read_b128 v[92:95], v253 offset:6144
	s_waitcnt lgkmcnt(14)
	v_mfma_f32_16x16x32_bf16 v[0:3], v[64:67], v[96:99], v[0:3]
	s_waitcnt lgkmcnt(13)
	v_mfma_f32_16x16x32_bf16 v[4:7], v[64:67], v[100:103], v[4:7]
	s_waitcnt lgkmcnt(12)
	v_mfma_f32_16x16x32_bf16 v[8:11], v[64:67], v[104:107], v[8:11]
	s_waitcnt lgkmcnt(11)
	v_mfma_f32_16x16x32_bf16 v[12:15], v[64:67], v[108:111], v[12:15]
	s_waitcnt lgkmcnt(10)
	v_mfma_f32_16x16x32_bf16 v[16:19], v[68:71], v[96:99], v[16:19]
	v_mfma_f32_16x16x32_bf16 v[20:23], v[68:71], v[100:103], v[20:23]
	v_mfma_f32_16x16x32_bf16 v[24:27], v[68:71], v[104:107], v[24:27]
	v_mfma_f32_16x16x32_bf16 v[28:31], v[68:71], v[108:111], v[28:31]
	s_waitcnt lgkmcnt(0)
	s_barrier
	s_add_u32 m0, s12, 0x0
	v_mfma_f32_16x16x32_bf16 v[32:35], v[72:75], v[96:99], v[32:35]
	global_load_lds_dwordx4 v248, s[8:9]
	s_add_u32 m0, s12, 0x400
	v_mfma_f32_16x16x32_bf16 v[36:39], v[72:75], v[100:103], v[36:39]
	global_load_lds_dwordx4 v249, s[8:9]
	s_add_u32 m0, s12, 0x800
	v_mfma_f32_16x16x32_bf16 v[40:43], v[72:75], v[104:107], v[40:43]
	global_load_lds_dwordx4 v250, s[8:9]
	s_add_u32 m0, s12, 0xc00
	v_mfma_f32_16x16x32_bf16 v[44:47], v[72:75], v[108:111], v[44:47]
	global_load_lds_dwordx4 v251, s[8:9]
	s_add_u32 m0, s12, 0x8000
	v_mfma_f32_16x16x32_bf16 v[48:51], v[76:79], v[96:99], v[48:51]
	global_load_lds_dwordx4 v248, s[10:11] sc1
	s_add_u32 m0, s12, 0x8400
	v_mfma_f32_16x16x32_bf16 v[52:55], v[76:79], v[100:103], v[52:55]
	global_load_lds_dwordx4 v249, s[10:11] sc1
	s_add_u32 m0, s12, 0x8800
	v_mfma_f32_16x16x32_bf16 v[56:59], v[76:79], v[104:107], v[56:59]
	global_load_lds_dwordx4 v250, s[10:11] sc1
	s_add_u32 m0, s12, 0x8c00
	v_mfma_f32_16x16x32_bf16 v[60:63], v[76:79], v[108:111], v[60:63]
	global_load_lds_dwordx4 v251, s[10:11] sc1
	s_add_u32 s8, s8, 0x80
	s_addc_u32 s9, s9, 0
	s_add_u32 s10, s10, 0x80
	s_addc_u32 s11, s11, 0
	s_waitcnt vmcnt(8)
	s_barrier
	ds_read_b128 v[64:67], v252 offset:16384
	ds_read_b128 v[96:99], v254 offset:49152
	ds_read_b128 v[100:103], v254 offset:51200
	ds_read_b128 v[104:107], v254 offset:53248
	ds_read_b128 v[108:111], v254 offset:55296
	ds_read_b128 v[68:71], v252 offset:18432
	ds_read_b128 v[72:75], v252 offset:20480
	ds_read_b128 v[76:79], v252 offset:22528
	v_mfma_f32_16x16x32_bf16 v[0:3], v[80:83], v[112:115], v[0:3]
	v_mfma_f32_16x16x32_bf16 v[4:7], v[80:83], v[116:119], v[4:7]
	v_mfma_f32_16x16x32_bf16 v[8:11], v[80:83], v[120:123], v[8:11]
	v_mfma_f32_16x16x32_bf16 v[12:15], v[80:83], v[124:127], v[12:15]
	v_mfma_f32_16x16x32_bf16 v[16:19], v[84:87], v[112:115], v[16:19]
	v_mfma_f32_16x16x32_bf16 v[20:23], v[84:87], v[116:119], v[20:23]
	v_mfma_f32_16x16x32_bf16 v[24:27], v[84:87], v[120:123], v[24:27]
	v_mfma_f32_16x16x32_bf16 v[28:31], v[84:87], v[124:127], v[28:31]
	v_mfma_f32_16x16x32_bf16 v[32:35], v[88:91], v[112:115], v[32:35]
	v_mfma_f32_16x16x32_bf16 v[36:39], v[88:91], v[116:119], v[36:39]
	v_mfma_f32_16x16x32_bf16 v[40:43], v[88:91], v[120:123], v[40:43]
	v_mfma_f32_16x16x32_bf16 v[44:47], v[88:91], v[124:127], v[44:47]
	v_mfma_f32_16x16x32_bf16 v[48:51], v[92:95], v[112:115], v[48:51]
	v_mfma_f32_16x16x32_bf16 v[52:55], v[92:95], v[116:119], v[52:55]
	v_mfma_f32_16x16x32_bf16 v[56:59], v[92:95], v[120:123], v[56:59]
	v_mfma_f32_16x16x32_bf16 v[60:63], v[92:95], v[124:127], v[60:63]
	ds_read_b128 v[80:83], v253 offset:16384
	ds_read_b128 v[112:115], v255 offset:49152
	ds_read_b128 v[116:119], v255 offset:51200
	ds_read_b128 v[120:123], v255 offset:53248
	ds_read_b128 v[124:127], v255 offset:55296
	ds_read_b128 v[84:87], v253 offset:18432
	ds_read_b128 v[88:91], v253 offset:20480
	ds_read_b128 v[92:95], v253 offset:22528
	s_waitcnt lgkmcnt(14)
	v_mfma_f32_16x16x32_bf16 v[0:3], v[64:67], v[96:99], v[0:3]
	s_waitcnt lgkmcnt(13)
	v_mfma_f32_16x16x32_bf16 v[4:7], v[64:67], v[100:103], v[4:7]
	s_waitcnt lgkmcnt(12)
	v_mfma_f32_16x16x32_bf16 v[8:11], v[64:67], v[104:107], v[8:11]
	s_waitcnt lgkmcnt(11)
	v_mfma_f32_16x16x32_bf16 v[12:15], v[64:67], v[108:111], v[12:15]
	s_waitcnt lgkmcnt(10)
	v_mfma_f32_16x16x32_bf16 v[16:19], v[68:71], v[96:99], v[16:19]
	v_mfma_f32_16x16x32_bf16 v[20:23], v[68:71], v[100:103], v[20:23]
	v_mfma_f32_16x16x32_bf16 v[24:27], v[68:71], v[104:107], v[24:27]
	v_mfma_f32_16x16x32_bf16 v[28:31], v[68:71], v[108:111], v[28:31]
	s_waitcnt lgkmcnt(0)
	s_barrier
	s_add_u32 m0, s12, 0x4000
	v_mfma_f32_16x16x32_bf16 v[32:35], v[72:75], v[96:99], v[32:35]
	global_load_lds_dwordx4 v248, s[8:9]
	s_add_u32 m0, s12, 0x4400
	v_mfma_f32_16x16x32_bf16 v[36:39], v[72:75], v[100:103], v[36:39]
	global_load_lds_dwordx4 v249, s[8:9]
	s_add_u32 m0, s12, 0x4800
	v_mfma_f32_16x16x32_bf16 v[40:43], v[72:75], v[104:107], v[40:43]
	global_load_lds_dwordx4 v250, s[8:9]
	s_add_u32 m0, s12, 0x4c00
	v_mfma_f32_16x16x32_bf16 v[44:47], v[72:75], v[108:111], v[44:47]
	global_load_lds_dwordx4 v251, s[8:9]
	s_add_u32 m0, s12, 0xc000
	v_mfma_f32_16x16x32_bf16 v[48:51], v[76:79], v[96:99], v[48:51]
	global_load_lds_dwordx4 v248, s[10:11] sc1
	s_add_u32 m0, s12, 0xc400
	v_mfma_f32_16x16x32_bf16 v[52:55], v[76:79], v[100:103], v[52:55]
	global_load_lds_dwordx4 v249, s[10:11] sc1
	s_add_u32 m0, s12, 0xc800
	v_mfma_f32_16x16x32_bf16 v[56:59], v[76:79], v[104:107], v[56:59]
	global_load_lds_dwordx4 v250, s[10:11] sc1
	s_add_u32 m0, s12, 0xcc00
	v_mfma_f32_16x16x32_bf16 v[60:63], v[76:79], v[108:111], v[60:63]
	global_load_lds_dwordx4 v251, s[10:11] sc1
	s_add_u32 s8, s8, 0x80
	s_addc_u32 s9, s9, 0
	s_add_u32 s10, s10, 0x80
	s_addc_u32 s11, s11, 0
	s_sub_u32 s13, s13, 1
	s_cmp_lg_u32 s13, 0
	s_cbranch_scc1 .Lr6_loop
	s_waitcnt vmcnt(8)
	s_barrier
	ds_read_b128 v[64:67], v252 offset:0
	ds_read_b128 v[96:99], v254 offset:32768
	ds_read_b128 v[100:103], v254 offset:34816
	ds_read_b128 v[104:107], v254 offset:36864
	ds_read_b128 v[108:111], v254 offset:38912
	ds_read_b128 v[68:71], v252 offset:2048
	ds_read_b128 v[72:75], v252 offset:4096
	ds_read_b128 v[76:79], v252 offset:6144
	v_mfma_f32_16x16x32_bf16 v[0:3], v[80:83], v[112:115], v[0:3]
	v_mfma_f32_16x16x32_bf16 v[4:7], v[80:83], v[116:119], v[4:7]
	v_mfma_f32_16x16x32_bf16 v[8:11], v[80:83], v[120:123], v[8:11]
	v_mfma_f32_16x16x32_bf16 v[12:15], v[80:83], v[124:127], v[12:15]
	v_mfma_f32_16x16x32_bf16 v[16:19], v[84:87], v[112:115], v[16:19]
	v_mfma_f32_16x16x32_bf16 v[20:23], v[84:87], v[116:119], v[20:23]
	v_mfma_f32_16x16x32_bf16 v[24:27], v[84:87], v[120:123], v[24:27]
	v_mfma_f32_16x16x32_bf16 v[28:31], v[84:87], v[124:127], v[28:31]
	v_mfma_f32_16x16x32_bf16 v[32:35], v[88:91], v[112:115], v[32:35]
	v_mfma_f32_16x16x32_bf16 v[36:39], v[88:91], v[116:119], v[36:39]
	v_mfma_f32_16x16x32_bf16 v[40:43], v[88:91], v[120:123], v[40:43]
	v_mfma_f32_16x16x32_bf16 v[44:47], v[88:91], v[124:127], v[44:47]
	v_mfma_f32_16x16x32_bf16 v[48:51], v[92:95], v[112:115], v[48:51]
	v_mfma_f32_16x16x32_bf16 v[52:55], v[92:95], v[116:119], v[52:55]
	v_mfma_f32_16x16x32_bf16 v[56:59], v[92:95], v[120:123], v[56:59]
	v_mfma_f32_16x16x32_bf16 v[60:63], v[92:95], v[124:127], v[60:63]
	ds_read_b128 v[80:83], v253 offset:0
	ds_read_b128 v[112:115], v255 offset:32768
	ds_read_b128 v[116:119], v255 offset:34816
	ds_read_b128 v[120:123], v255 offset:36864
	ds_read_b128 v[124:127], v255 offset:38912
	ds_read_b128 v[84:87], v253 offset:2048
	ds_read_b128 v[88:91], v253 offset:4096
	ds_read_b128 v[92:95], v253 offset:6144
	s_waitcnt lgkmcnt(14)
	v_mfma_f32_16x16x32_bf16 v[0:3], v[64:67], v[96:99], v[0:3]
	s_waitcnt lgkmcnt(13)
	v_mfma_f32_16x16x32_bf16 v[4:7], v[64:67], v[100:103], v[4:7]
	s_waitcnt lgkmcnt(12)
	v_mfma_f32_16x16x32_bf16 v[8:11], v[64:67], v[104:107], v[8:11]
	s_waitcnt lgkmcnt(11)
	v_mfma_f32_16x16x32_bf16 v[12:15], v[64:67], v[108:111], v[12:15]
	s_waitcnt lgkmcnt(10)
	v_mfma_f32_16x16x32_bf16 v[16:19], v[68:71], v[96:99], v[16:19]
	v_mfma_f32_16x16x32_bf16 v[20:23], v[68:71], v[100:103], v[20:23]
	v_mfma_f32_16x16x32_bf16 v[24:27], v[68:71], v[104:107], v[24:27]
	v_mfma_f32_16x16x32_bf16 v[28:31], v[68:71], v[108:111], v[28:31]
	s_waitcnt lgkmcnt(0)
	s_barrier
	v_mfma_f32_16x16x32_bf16 v[32:35], v[72:75], v[96:99], v[32:35]
	v_mfma_f32_16x16x32_bf16 v[36:39], v[72:75], v[100:103], v[36:39]
	v_mfma_f32_16x16x32_bf16 v[40:43], v[72:75], v[104:107], v[40:43]
	v_mfma_f32_16x16x32_bf16 v[44:47], v[72:75], v[108:111], v[44:47]
	v_mfma_f32_16x16x32_bf16 v[48:51], v[76:79], v[96:99], v[48:51]
	v_mfma_f32_16x16x32_bf16 v[52:55], v[76:79], v[100:103], v[52:55]
	v_mfma_f32_16x16x32_bf16 v[56:59], v[76:79], v[104:107], v[56:59]
	v_mfma_f32_16x16x32_bf16 v[60:63], v[76:79], v[108:111], v[60:63]
	s_waitcnt vmcnt(0)
	s_barrier
	ds_read_b128 v[64:67], v252 offset:16384
	ds_read_b128 v[96:99], v254 offset:49152
	ds_read_b128 v[100:103], v254 offset:51200
	ds_read_b128 v[104:107], v254 offset:53248
	ds_read_b128 v[108:111], v254 offset:55296
	ds_read_b128 v[68:71], v252 offset:18432
	ds_read_b128 v[72:75], v252 offset:20480
	ds_read_b128 v[76:79], v252 offset:22528
	v_mfma_f32_16x16x32_bf16 v[0:3], v[80:83], v[112:115], v[0:3]
	v_mfma_f32_16x16x32_bf16 v[4:7], v[80:83], v[116:119], v[4:7]
	v_mfma_f32_16x16x32_bf16 v[8:11], v[80:83], v[120:123], v[8:11]
	v_mfma_f32_16x16x32_bf16 v[12:15], v[80:83], v[124:127], v[12:15]
	v_mfma_f32_16x16x32_bf16 v[16:19], v[84:87], v[112:115], v[16:19]
	v_mfma_f32_16x16x32_bf16 v[20:23], v[84:87], v[116:119], v[20:23]
	v_mfma_f32_16x16x32_bf16 v[24:27], v[84:87], v[120:123], v[24:27]
	v_mfma_f32_16x16x32_bf16 v[28:31], v[84:87], v[124:127], v[28:31]
	v_mfma_f32_16x16x32_bf16 v[32:35], v[88:91], v[112:115], v[32:35]
	v_mfma_f32_16x16x32_bf16 v[36:39], v[88:91], v[116:119], v[36:39]
	v_mfma_f32_16x16x32_bf16 v[40:43], v[88:91], v[120:123], v[40:43]
	v_mfma_f32_16x16x32_bf16 v[44:47], v[88:91], v[124:127], v[44:47]
	v_mfma_f32_16x16x32_bf16 v[48:51], v[92:95], v[112:115], v[48:51]
	v_mfma_f32_16x16x32_bf16 v[52:55], v[92:95], v[116:119], v[52:55]
	v_mfma_f32_16x16x32_bf16 v[56:59], v[92:95], v[120:123], v[56:59]
	v_mfma_f32_16x16x32_bf16 v[60:63], v[92:95], v[124:127], v[60:63]
	ds_read_b128 v[80:83], v253 offset:16384
	ds_read_b128 v[112:115], v255 offset:49152
	ds_read_b128 v[116:119], v255 offset:51200
	ds_read_b128 v[120:123], v255 offset:53248
	ds_read_b128 v[124:127], v255 offset:55296
	ds_read_b128 v[84:87], v253 offset:18432
	ds_read_b128 v[88:91], v253 offset:20480
	ds_read_b128 v[92:95], v253 offset:22528
	s_waitcnt lgkmcnt(14)
	v_mfma_f32_16x16x32_bf16 v[0:3], v[64:67], v[96:99], v[0:3]
	s_waitcnt lgkmcnt(13)
	v_mfma_f32_16x16x32_bf16 v[4:7], v[64:67], v[100:103], v[4:7]
	s_waitcnt lgkmcnt(12)
	v_mfma_f32_16x16x32_bf16 v[8:11], v[64:67], v[104:107], v[8:11]
	s_waitcnt lgkmcnt(11)
	v_mfma_f32_16x16x32_bf16 v[12:15], v[64:67], v[108:111], v[12:15]
	s_waitcnt lgkmcnt(10)
	v_mfma_f32_16x16x32_bf16 v[16:19], v[68:71], v[96:99], v[16:19]
	v_mfma_f32_16x16x32_bf16 v[20:23], v[68:71], v[100:103], v[20:23]
	v_mfma_f32_16x16x32_bf16 v[24:27], v[68:71], v[104:107], v[24:27]
	v_mfma_f32_16x16x32_bf16 v[28:31], v[68:71], v[108:111], v[28:31]
	s_waitcnt lgkmcnt(0)
	s_barrier
	v_mfma_f32_16x16x32_bf16 v[32:35], v[72:75], v[96:99], v[32:35]
	v_mfma_f32_16x16x32_bf16 v[36:39], v[72:75], v[100:103], v[36:39]
	v_mfma_f32_16x16x32_bf16 v[40:43], v[72:75], v[104:107], v[40:43]
	v_mfma_f32_16x16x32_bf16 v[44:47], v[72:75], v[108:111], v[44:47]
	v_mfma_f32_16x16x32_bf16 v[48:51], v[76:79], v[96:99], v[48:51]
	v_mfma_f32_16x16x32_bf16 v[52:55], v[76:79], v[100:103], v[52:55]
	v_mfma_f32_16x16x32_bf16 v[56:59], v[76:79], v[104:107], v[56:59]
	v_mfma_f32_16x16x32_bf16 v[60:63], v[76:79], v[108:111], v[60:63]
	v_mfma_f32_16x16x32_bf16 v[0:3], v[80:83], v[112:115], v[0:3]
	v_mfma_f32_16x16x32_bf16 v[4:7], v[80:83], v[116:119], v[4:7]
	v_mfma_f32_16x16x32_bf16 v[8:11], v[80:83], v[120:123], v[8:11]
	v_mfma_f32_16x16x32_bf16 v[12:15], v[80:83], v[124:127], v[12:15]
	v_mfma_f32_16x16x32_bf16 v[16:19], v[84:87], v[112:115], v[16:19]
	v_mfma_f32_16x16x32_bf16 v[20:23], v[84:87], v[116:119], v[20:23]
	v_mfma_f32_16x16x32_bf16 v[24:27], v[84:87], v[120:123], v[24:27]
	v_mfma_f32_16x16x32_bf16 v[28:31], v[84:87], v[124:127], v[28:31]
	v_mfma_f32_16x16x32_bf16 v[32:35], v[88:91], v[112:115], v[32:35]
	v_mfma_f32_16x16x32_bf16 v[36:39], v[88:91], v[116:119], v[36:39]
	v_mfma_f32_16x16x32_bf16 v[40:43], v[88:91], v[120:123], v[40:43]
	v_mfma_f32_16x16x32_bf16 v[44:47], v[88:91], v[124:127], v[44:47]
	v_mfma_f32_16x16x32_bf16 v[48:51], v[92:95], v[112:115], v[48:51]
	v_mfma_f32_16x16x32_bf16 v[52:55], v[92:95], v[116:119], v[52:55]
	v_mfma_f32_16x16x32_bf16 v[56:59], v[92:95], v[120:123], v[56:59]
	v_mfma_f32_16x16x32_bf16 v[60:63], v[92:95], v[124:127], v[60:63]
	s_nop 7
	s_nop 1
	s_mov_b64 s[18:19], s[20:21]
	v_fma_f32 v129, v201, v0, v129
	v_fma_f32 v130, v202, v4, v130
	v_fma_f32 v131, v203, v8, v131
	v_fma_f32 v132, v204, v12, v132
	global_store_dword v246, v129, s[18:19] offset:0 sc0 sc1
	global_store_dword v246, v130, s[18:19] offset:64 sc0 sc1
	global_store_dword v246, v131, s[18:19] offset:128 sc0 sc1
	global_store_dword v246, v132, s[18:19] offset:192 sc0 sc1
	s_add_u32 s18, s18, 0x1000
	s_addc_u32 s19, s19, 0
	v_fma_f32 v133, v201, v1, v133
	v_fma_f32 v134, v202, v5, v134
	v_fma_f32 v135, v203, v9, v135
	v_fma_f32 v136, v204, v13, v136
	global_store_dword v246, v133, s[18:19] offset:0 sc0 sc1
	global_store_dword v246, v134, s[18:19] offset:64 sc0 sc1
	global_store_dword v246, v135, s[18:19] offset:128 sc0 sc1
	global_store_dword v246, v136, s[18:19] offset:192 sc0 sc1
	s_add_u32 s18, s18, 0x1000
	s_addc_u32 s19, s19, 0
	v_fma_f32 v137, v201, v2, v137
	v_fma_f32 v138, v202, v6, v138
	v_fma_f32 v139, v203, v10, v139
	v_fma_f32 v140, v204, v14, v140
	global_store_dword v246, v137, s[18:19] offset:0 sc0 sc1
	global_store_dword v246, v138, s[18:19] offset:64 sc0 sc1
	global_store_dword v246, v139, s[18:19] offset:128 sc0 sc1
	global_store_dword v246, v140, s[18:19] offset:192 sc0 sc1
	s_add_u32 s18, s18, 0x1000
	s_addc_u32 s19, s19, 0
	v_fma_f32 v141, v201, v3, v141
	v_fma_f32 v142, v202, v7, v142
	v_fma_f32 v143, v203, v11, v143
	v_fma_f32 v144, v204, v15, v144
	global_store_dword v246, v141, s[18:19] offset:0 sc0 sc1
	global_store_dword v246, v142, s[18:19] offset:64 sc0 sc1
	global_store_dword v246, v143, s[18:19] offset:128 sc0 sc1
	global_store_dword v246, v144, s[18:19] offset:192 sc0 sc1
	s_add_u32 s18, s18, 0xd000
	s_addc_u32 s19, s19, 0
	v_fma_f32 v145, v201, v16, v145
	v_fma_f32 v146, v202, v20, v146
	v_fma_f32 v147, v203, v24, v147
	v_fma_f32 v148, v204, v28, v148
	global_store_dword v246, v145, s[18:19] offset:0 sc0 sc1
	global_store_dword v246, v146, s[18:19] offset:64 sc0 sc1
	global_store_dword v246, v147, s[18:19] offset:128 sc0 sc1
	global_store_dword v246, v148, s[18:19] offset:192 sc0 sc1
	s_add_u32 s18, s18, 0x1000
	s_addc_u32 s19, s19, 0
	v_fma_f32 v149, v201, v17, v149
	v_fma_f32 v150, v202, v21, v150
	v_fma_f32 v151, v203, v25, v151
	v_fma_f32 v152, v204, v29, v152
	global_store_dword v246, v149, s[18:19] offset:0 sc0 sc1
	global_store_dword v246, v150, s[18:19] offset:64 sc0 sc1
	global_store_dword v246, v151, s[18:19] offset:128 sc0 sc1
	global_store_dword v246, v152, s[18:19] offset:192 sc0 sc1
	s_add_u32 s18, s18, 0x1000
	s_addc_u32 s19, s19, 0
	v_fma_f32 v153, v201, v18, v153
	v_fma_f32 v154, v202, v22, v154
	v_fma_f32 v155, v203, v26, v155
	v_fma_f32 v156, v204, v30, v156
	global_store_dword v246, v153, s[18:19] offset:0 sc0 sc1
	global_store_dword v246, v154, s[18:19] offset:64 sc0 sc1
	global_store_dword v246, v155, s[18:19] offset:128 sc0 sc1
	global_store_dword v246, v156, s[18:19] offset:192 sc0 sc1
	s_add_u32 s18, s18, 0x1000
	s_addc_u32 s19, s19, 0
	v_fma_f32 v157, v201, v19, v157
	v_fma_f32 v158, v202, v23, v158
	v_fma_f32 v159, v203, v27, v159
	v_fma_f32 v160, v204, v31, v160
	global_store_dword v246, v157, s[18:19] offset:0 sc0 sc1
	global_store_dword v246, v158, s[18:19] offset:64 sc0 sc1
	global_store_dword v246, v159, s[18:19] offset:128 sc0 sc1
	global_store_dword v246, v160, s[18:19] offset:192 sc0 sc1
	s_add_u32 s18, s18, 0xd000
	s_addc_u32 s19, s19, 0
	v_fma_f32 v161, v201, v32, v161
	v_fma_f32 v170, v202, v36, v170
	v_fma_f32 v171, v203, v40, v171
	v_fma_f32 v172, v204, v44, v172
	global_store_dword v246, v161, s[18:19] offset:0 sc0 sc1
	global_store_dword v246, v170, s[18:19] offset:64 sc0 sc1
	global_store_dword v246, v171, s[18:19] offset:128 sc0 sc1
	global_store_dword v246, v172, s[18:19] offset:192 sc0 sc1
	s_add_u32 s18, s18, 0x1000
	s_addc_u32 s19, s19, 0
	v_fma_f32 v173, v201, v33, v173
	v_fma_f32 v174, v202, v37, v174
	v_fma_f32 v175, v203, v41, v175
	v_fma_f32 v176, v204, v45, v176
	global_store_dword v246, v173, s[18:19] offset:0 sc0 sc1
	global_store_dword v246, v174, s[18:19] offset:64 sc0 sc1
	global_store_dword v246, v175, s[18:19] offset:128 sc0 sc1
	global_store_dword v246, v176, s[18:19] offset:192 sc0 sc1
	s_add_u32 s18, s18, 0x1000
	s_addc_u32 s19, s19, 0
	v_fma_f32 v177, v201, v34, v177
	v_fma_f32 v178, v202, v38, v178
	v_fma_f32 v179, v203, v42, v179
	v_fma_f32 v180, v204, v46, v180
	global_store_dword v246, v177, s[18:19] offset:0 sc0 sc1
	global_store_dword v246, v178, s[18:19] offset:64 sc0 sc1
	global_store_dword v246, v179, s[18:19] offset:128 sc0 sc1
	global_store_dword v246, v180, s[18:19] offset:192 sc0 sc1
	s_add_u32 s18, s18, 0x1000
	s_addc_u32 s19, s19, 0
	v_fma_f32 v181, v201, v35, v181
	v_fma_f32 v182, v202, v39, v182
	v_fma_f32 v183, v203, v43, v183
	v_fma_f32 v184, v204, v47, v184
	global_store_dword v246, v181, s[18:19] offset:0 sc0 sc1
	global_store_dword v246, v182, s[18:19] offset:64 sc0 sc1
	global_store_dword v246, v183, s[18:19] offset:128 sc0 sc1
	global_store_dword v246, v184, s[18:19] offset:192 sc0 sc1
	s_add_u32 s18, s18, 0xd000
	s_addc_u32 s19, s19, 0
	v_fma_f32 v185, v201, v48, v185
	v_fma_f32 v186, v202, v52, v186
	v_fma_f32 v187, v203, v56, v187
	v_fma_f32 v188, v204, v60, v188
	global_store_dword v246, v185, s[18:19] offset:0 sc0 sc1
	global_store_dword v246, v186, s[18:19] offset:64 sc0 sc1
	global_store_dword v246, v187, s[18:19] offset:128 sc0 sc1
	global_store_dword v246, v188, s[18:19] offset:192 sc0 sc1
	s_add_u32 s18, s18, 0x1000
	s_addc_u32 s19, s19, 0
	v_fma_f32 v189, v201, v49, v189
	v_fma_f32 v190, v202, v53, v190
	v_fma_f32 v191, v203, v57, v191
	v_fma_f32 v192, v204, v61, v192
	global_store_dword v246, v189, s[18:19] offset:0 sc0 sc1
	global_store_dword v246, v190, s[18:19] offset:64 sc0 sc1
	global_store_dword v246, v191, s[18:19] offset:128 sc0 sc1
	global_store_dword v246, v192, s[18:19] offset:192 sc0 sc1
	s_add_u32 s18, s18, 0x1000
	s_addc_u32 s19, s19, 0
	v_fma_f32 v193, v201, v50, v193
	v_fma_f32 v194, v202, v54, v194
	v_fma_f32 v195, v203, v58, v195
	v_fma_f32 v196, v204, v62, v196
	global_store_dword v246, v193, s[18:19] offset:0 sc0 sc1
	global_store_dword v246, v194, s[18:19] offset:64 sc0 sc1
	global_store_dword v246, v195, s[18:19] offset:128 sc0 sc1
	global_store_dword v246, v196, s[18:19] offset:192 sc0 sc1
	s_add_u32 s18, s18, 0x1000
	s_addc_u32 s19, s19, 0
	v_fma_f32 v197, v201, v51, v197
	v_fma_f32 v198, v202, v55, v198
	v_fma_f32 v199, v203, v59, v199
	v_fma_f32 v200, v204, v63, v200
	global_store_dword v246, v197, s[18:19] offset:0 sc0 sc1
	global_store_dword v246, v198, s[18:19] offset:64 sc0 sc1
	global_store_dword v246, v199, s[18:19] offset:128 sc0 sc1
	global_store_dword v246, v200, s[18:19] offset:192 sc0 sc1
	s_add_u32 s15, s15, s16
	s_branch .Lr6_tile

.Lf8_tile:
	s_cmp_lt_u32 s15, 0xb00
	s_cbranch_scc0 .Lf8_end
	s_and_b32 s2, s15, 63
	s_lshr_b32 s3, s15, 6
	s_lshl_b32 s14, s2, 18
	s_add_u32 s8, s26, s14
	s_addc_u32 s9, s27, 0
	s_lshl_b32 s14, s3, 18
	s_add_u32 s10, s28, s14
	s_addc_u32 s11, s29, 0
	s_mul_i32 s14, s2, 0xb0000
	s_lshl_b32 s6, s3, 7
	s_add_u32 s14, s14, s6
	s_add_u32 s20, s4, 0x9b7a100
	s_addc_u32 s21, s5, 0
	s_add_u32 s20, s20, s14
	s_addc_u32 s21, s21, 0
	v_readfirstlane_b32 s12, v247
	s_nop 3
	s_lshl_b32 s12, s12, 12
	s_lshr_b32 s14, s58, 3
	s_and_b32 s14, s14, 15
	s_sub_u32 s23, 16, s14
	s_lshl_b32 s14, s14, 7
	s_add_u32 s8, s8, s14
	s_addc_u32 s9, s9, 0
	s_add_u32 s10, s10, s14
	s_addc_u32 s11, s11, 0
	s_add_u32 m0, s12, 0x0
	v_mov_b32_e32 v0, 0
	global_load_lds_dwordx4 v248, s[8:9]
	v_mov_b32_e32 v1, 0
	s_add_u32 m0, s12, 0x400
	v_mov_b32_e32 v2, 0
	global_load_lds_dwordx4 v249, s[8:9]
	v_mov_b32_e32 v3, 0
	s_add_u32 m0, s12, 0x800
	v_mov_b32_e32 v4, 0
	global_load_lds_dwordx4 v250, s[8:9]
	v_mov_b32_e32 v5, 0
	s_add_u32 m0, s12, 0xc00
	v_mov_b32_e32 v6, 0
	global_load_lds_dwordx4 v251, s[8:9]
	v_mov_b32_e32 v7, 0
	s_add_u32 m0, s12, 0x8000
	v_mov_b32_e32 v8, 0
	global_load_lds_dwordx4 v248, s[10:11] sc1
	v_mov_b32_e32 v9, 0
	s_add_u32 m0, s12, 0x8400
	v_mov_b32_e32 v10, 0
	global_load_lds_dwordx4 v249, s[10:11] sc1
	v_mov_b32_e32 v11, 0
	s_add_u32 m0, s12, 0x8800
	v_mov_b32_e32 v12, 0
	global_load_lds_dwordx4 v250, s[10:11] sc1
	v_mov_b32_e32 v13, 0
	s_add_u32 m0, s12, 0x8c00
	v_mov_b32_e32 v14, 0
	global_load_lds_dwordx4 v251, s[10:11] sc1
	v_mov_b32_e32 v15, 0
	s_sub_u32 s23, s23, 1
	s_cmp_eq_u32 s23, 0
	s_cselect_b32 s14, 0x800, 0
	s_sub_u32 s8, s8, s14
	s_subb_u32 s9, s9, 0
	s_add_u32 s8, s8, 0x80
	s_addc_u32 s9, s9, 0
	s_sub_u32 s10, s10, s14
	s_subb_u32 s11, s11, 0
	s_add_u32 s10, s10, 0x80
	s_addc_u32 s11, s11, 0
	s_add_u32 m0, s12, 0x4000
	v_mov_b32_e32 v16, 0
	global_load_lds_dwordx4 v248, s[8:9]
	v_mov_b32_e32 v17, 0
	s_add_u32 m0, s12, 0x4400
	v_mov_b32_e32 v18, 0
	global_load_lds_dwordx4 v249, s[8:9]
	v_mov_b32_e32 v19, 0
	s_add_u32 m0, s12, 0x4800
	v_mov_b32_e32 v20, 0
	global_load_lds_dwordx4 v250, s[8:9]
	v_mov_b32_e32 v21, 0
	s_add_u32 m0, s12, 0x4c00
	v_mov_b32_e32 v22, 0
	global_load_lds_dwordx4 v251, s[8:9]
	v_mov_b32_e32 v23, 0
	s_add_u32 m0, s12, 0xc000
	v_mov_b32_e32 v24, 0
	global_load_lds_dwordx4 v248, s[10:11] sc1
	v_mov_b32_e32 v25, 0
	s_add_u32 m0, s12, 0xc400
	v_mov_b32_e32 v26, 0
	global_load_lds_dwordx4 v249, s[10:11] sc1
	v_mov_b32_e32 v27, 0
	s_add_u32 m0, s12, 0xc800
	v_mov_b32_e32 v28, 0
	global_load_lds_dwordx4 v250, s[10:11] sc1
	v_mov_b32_e32 v29, 0
	s_add_u32 m0, s12, 0xcc00
	v_mov_b32_e32 v30, 0
	global_load_lds_dwordx4 v251, s[10:11] sc1
	v_mov_b32_e32 v31, 0
	s_sub_u32 s23, s23, 1
	s_cmp_eq_u32 s23, 0
	s_cselect_b32 s14, 0x800, 0
	s_sub_u32 s8, s8, s14
	s_subb_u32 s9, s9, 0
	s_add_u32 s8, s8, 0x80
	s_addc_u32 s9, s9, 0
	s_sub_u32 s10, s10, s14
	s_subb_u32 s11, s11, 0
	s_add_u32 s10, s10, 0x80
	s_addc_u32 s11, s11, 0
	v_mov_b32_e32 v32, 0
	v_mov_b32_e32 v33, 0
	v_mov_b32_e32 v34, 0
	v_mov_b32_e32 v35, 0
	v_mov_b32_e32 v36, 0
	v_mov_b32_e32 v37, 0
	v_mov_b32_e32 v38, 0
	v_mov_b32_e32 v39, 0
	v_mov_b32_e32 v40, 0
	v_mov_b32_e32 v41, 0
	v_mov_b32_e32 v42, 0
	v_mov_b32_e32 v43, 0
	v_mov_b32_e32 v44, 0
	v_mov_b32_e32 v45, 0
	v_mov_b32_e32 v46, 0
	v_mov_b32_e32 v47, 0
	v_mov_b32_e32 v48, 0
	v_mov_b32_e32 v49, 0
	v_mov_b32_e32 v50, 0
	v_mov_b32_e32 v51, 0
	v_mov_b32_e32 v52, 0
	v_mov_b32_e32 v53, 0
	v_mov_b32_e32 v54, 0
	v_mov_b32_e32 v55, 0
	v_mov_b32_e32 v56, 0
	v_mov_b32_e32 v57, 0
	v_mov_b32_e32 v58, 0
	v_mov_b32_e32 v59, 0
	v_mov_b32_e32 v60, 0
	v_mov_b32_e32 v61, 0
	v_mov_b32_e32 v62, 0
	v_mov_b32_e32 v63, 0
	s_waitcnt vmcnt(8)
	s_barrier
	ds_read_b128 v[64:67], v252 offset:0
	ds_read_b128 v[96:99], v254 offset:32768
	ds_read_b128 v[100:103], v254 offset:34816
	ds_read_b128 v[104:107], v254 offset:36864
	ds_read_b128 v[108:111], v254 offset:38912
	ds_read_b128 v[68:71], v252 offset:2048
	ds_read_b128 v[72:75], v252 offset:4096
	ds_read_b128 v[76:79], v252 offset:6144
	ds_read_b128 v[80:83], v253 offset:0
	ds_read_b128 v[112:115], v255 offset:32768
	ds_read_b128 v[116:119], v255 offset:34816
	ds_read_b128 v[120:123], v255 offset:36864
	ds_read_b128 v[124:127], v255 offset:38912
	s_waitcnt lgkmcnt(11)
	v_mfma_f32_16x16x32_bf16 v[0:3], v[96:99], v[64:67], v[0:3]
	s_waitcnt lgkmcnt(10)
	v_mfma_f32_16x16x32_bf16 v[4:7], v[100:103], v[64:67], v[4:7]
	s_waitcnt lgkmcnt(9)
	v_mfma_f32_16x16x32_bf16 v[8:11], v[104:107], v[64:67], v[8:11]
	s_waitcnt lgkmcnt(8)
	v_mfma_f32_16x16x32_bf16 v[12:15], v[108:111], v[64:67], v[12:15]
	ds_read_b128 v[84:87], v253 offset:2048
	ds_read_b128 v[88:91], v253 offset:4096
	ds_read_b128 v[92:95], v253 offset:6144
	s_waitcnt lgkmcnt(10)
	v_mfma_f32_16x16x32_bf16 v[16:19], v[96:99], v[68:71], v[16:19]
	v_mfma_f32_16x16x32_bf16 v[20:23], v[100:103], v[68:71], v[20:23]
	v_mfma_f32_16x16x32_bf16 v[24:27], v[104:107], v[68:71], v[24:27]
	v_mfma_f32_16x16x32_bf16 v[28:31], v[108:111], v[68:71], v[28:31]
	s_waitcnt lgkmcnt(0)
	s_barrier
	s_add_u32 m0, s12, 0x0
	v_mfma_f32_16x16x32_bf16 v[32:35], v[96:99], v[72:75], v[32:35]
	global_load_lds_dwordx4 v248, s[8:9]
	s_add_u32 m0, s12, 0x400
	v_mfma_f32_16x16x32_bf16 v[36:39], v[100:103], v[72:75], v[36:39]
	global_load_lds_dwordx4 v249, s[8:9]
	s_add_u32 m0, s12, 0x800
	v_mfma_f32_16x16x32_bf16 v[40:43], v[104:107], v[72:75], v[40:43]
	global_load_lds_dwordx4 v250, s[8:9]
	s_add_u32 m0, s12, 0xc00
	v_mfma_f32_16x16x32_bf16 v[44:47], v[108:111], v[72:75], v[44:47]
	global_load_lds_dwordx4 v251, s[8:9]
	s_add_u32 m0, s12, 0x8000
	v_mfma_f32_16x16x32_bf16 v[48:51], v[96:99], v[76:79], v[48:51]
	global_load_lds_dwordx4 v248, s[10:11] sc1
	s_add_u32 m0, s12, 0x8400
	v_mfma_f32_16x16x32_bf16 v[52:55], v[100:103], v[76:79], v[52:55]
	global_load_lds_dwordx4 v249, s[10:11] sc1
	s_add_u32 m0, s12, 0x8800
	v_mfma_f32_16x16x32_bf16 v[56:59], v[104:107], v[76:79], v[56:59]
	global_load_lds_dwordx4 v250, s[10:11] sc1
	s_add_u32 m0, s12, 0x8c00
	v_mfma_f32_16x16x32_bf16 v[60:63], v[108:111], v[76:79], v[60:63]
	global_load_lds_dwordx4 v251, s[10:11] sc1
	s_sub_u32 s23, s23, 1
	s_cmp_eq_u32 s23, 0
	s_cselect_b32 s14, 0x800, 0
	s_sub_u32 s8, s8, s14
	s_subb_u32 s9, s9, 0
	s_add_u32 s8, s8, 0x80
	s_addc_u32 s9, s9, 0
	s_sub_u32 s10, s10, s14
	s_subb_u32 s11, s11, 0
	s_add_u32 s10, s10, 0x80
	s_addc_u32 s11, s11, 0
	s_waitcnt vmcnt(8)
	s_barrier
	ds_read_b128 v[64:67], v252 offset:16384
	ds_read_b128 v[96:99], v254 offset:49152
	ds_read_b128 v[100:103], v254 offset:51200
	ds_read_b128 v[104:107], v254 offset:53248
	ds_read_b128 v[108:111], v254 offset:55296
	ds_read_b128 v[68:71], v252 offset:18432
	ds_read_b128 v[72:75], v252 offset:20480
	ds_read_b128 v[76:79], v252 offset:22528
	v_mfma_f32_16x16x32_bf16 v[0:3], v[112:115], v[80:83], v[0:3]
	v_mfma_f32_16x16x32_bf16 v[4:7], v[116:119], v[80:83], v[4:7]
	v_mfma_f32_16x16x32_bf16 v[8:11], v[120:123], v[80:83], v[8:11]
	v_mfma_f32_16x16x32_bf16 v[12:15], v[124:127], v[80:83], v[12:15]
	v_mfma_f32_16x16x32_bf16 v[16:19], v[112:115], v[84:87], v[16:19]
	v_mfma_f32_16x16x32_bf16 v[20:23], v[116:119], v[84:87], v[20:23]
	v_mfma_f32_16x16x32_bf16 v[24:27], v[120:123], v[84:87], v[24:27]
	v_mfma_f32_16x16x32_bf16 v[28:31], v[124:127], v[84:87], v[28:31]
	v_mfma_f32_16x16x32_bf16 v[32:35], v[112:115], v[88:91], v[32:35]
	v_mfma_f32_16x16x32_bf16 v[36:39], v[116:119], v[88:91], v[36:39]
	v_mfma_f32_16x16x32_bf16 v[40:43], v[120:123], v[88:91], v[40:43]
	v_mfma_f32_16x16x32_bf16 v[44:47], v[124:127], v[88:91], v[44:47]
	v_mfma_f32_16x16x32_bf16 v[48:51], v[112:115], v[92:95], v[48:51]
	v_mfma_f32_16x16x32_bf16 v[52:55], v[116:119], v[92:95], v[52:55]
	v_mfma_f32_16x16x32_bf16 v[56:59], v[120:123], v[92:95], v[56:59]
	v_mfma_f32_16x16x32_bf16 v[60:63], v[124:127], v[92:95], v[60:63]
	ds_read_b128 v[80:83], v253 offset:16384
	ds_read_b128 v[112:115], v255 offset:49152
	ds_read_b128 v[116:119], v255 offset:51200
	ds_read_b128 v[120:123], v255 offset:53248
	ds_read_b128 v[124:127], v255 offset:55296
	ds_read_b128 v[84:87], v253 offset:18432
	ds_read_b128 v[88:91], v253 offset:20480
	ds_read_b128 v[92:95], v253 offset:22528
	s_waitcnt lgkmcnt(14)
	v_mfma_f32_16x16x32_bf16 v[0:3], v[96:99], v[64:67], v[0:3]
	s_waitcnt lgkmcnt(13)
	v_mfma_f32_16x16x32_bf16 v[4:7], v[100:103], v[64:67], v[4:7]
	s_waitcnt lgkmcnt(12)
	v_mfma_f32_16x16x32_bf16 v[8:11], v[104:107], v[64:67], v[8:11]
	s_waitcnt lgkmcnt(11)
	v_mfma_f32_16x16x32_bf16 v[12:15], v[108:111], v[64:67], v[12:15]
	s_waitcnt lgkmcnt(10)
	v_mfma_f32_16x16x32_bf16 v[16:19], v[96:99], v[68:71], v[16:19]
	v_mfma_f32_16x16x32_bf16 v[20:23], v[100:103], v[68:71], v[20:23]
	v_mfma_f32_16x16x32_bf16 v[24:27], v[104:107], v[68:71], v[24:27]
	v_mfma_f32_16x16x32_bf16 v[28:31], v[108:111], v[68:71], v[28:31]
	s_waitcnt lgkmcnt(0)
	s_barrier
	s_add_u32 m0, s12, 0x4000
	v_mfma_f32_16x16x32_bf16 v[32:35], v[96:99], v[72:75], v[32:35]
	global_load_lds_dwordx4 v248, s[8:9]
	s_add_u32 m0, s12, 0x4400
	v_mfma_f32_16x16x32_bf16 v[36:39], v[100:103], v[72:75], v[36:39]
	global_load_lds_dwordx4 v249, s[8:9]
	s_add_u32 m0, s12, 0x4800
	v_mfma_f32_16x16x32_bf16 v[40:43], v[104:107], v[72:75], v[40:43]
	global_load_lds_dwordx4 v250, s[8:9]
	s_add_u32 m0, s12, 0x4c00
	v_mfma_f32_16x16x32_bf16 v[44:47], v[108:111], v[72:75], v[44:47]
	global_load_lds_dwordx4 v251, s[8:9]
	s_add_u32 m0, s12, 0xc000
	v_mfma_f32_16x16x32_bf16 v[48:51], v[96:99], v[76:79], v[48:51]
	global_load_lds_dwordx4 v248, s[10:11] sc1
	s_add_u32 m0, s12, 0xc400
	v_mfma_f32_16x16x32_bf16 v[52:55], v[100:103], v[76:79], v[52:55]
	global_load_lds_dwordx4 v249, s[10:11] sc1
	s_add_u32 m0, s12, 0xc800
	v_mfma_f32_16x16x32_bf16 v[56:59], v[104:107], v[76:79], v[56:59]
	global_load_lds_dwordx4 v250, s[10:11] sc1
	s_add_u32 m0, s12, 0xcc00
	v_mfma_f32_16x16x32_bf16 v[60:63], v[108:111], v[76:79], v[60:63]
	global_load_lds_dwordx4 v251, s[10:11] sc1
	s_sub_u32 s23, s23, 1
	s_cmp_eq_u32 s23, 0
	s_cselect_b32 s14, 0x800, 0
	s_sub_u32 s8, s8, s14
	s_subb_u32 s9, s9, 0
	s_add_u32 s8, s8, 0x80
	s_addc_u32 s9, s9, 0
	s_sub_u32 s10, s10, s14
	s_subb_u32 s11, s11, 0
	s_add_u32 s10, s10, 0x80
	s_addc_u32 s11, s11, 0
	s_mov_b32 s13, 6
.Lf8_loop:
	s_waitcnt vmcnt(8)
	s_barrier
	ds_read_b128 v[64:67], v252 offset:0
	ds_read_b128 v[96:99], v254 offset:32768
	ds_read_b128 v[100:103], v254 offset:34816
	ds_read_b128 v[104:107], v254 offset:36864
	ds_read_b128 v[108:111], v254 offset:38912
	ds_read_b128 v[68:71], v252 offset:2048
	ds_read_b128 v[72:75], v252 offset:4096
	ds_read_b128 v[76:79], v252 offset:6144
	v_mfma_f32_16x16x32_bf16 v[0:3], v[112:115], v[80:83], v[0:3]
	v_mfma_f32_16x16x32_bf16 v[4:7], v[116:119], v[80:83], v[4:7]
	v_mfma_f32_16x16x32_bf16 v[8:11], v[120:123], v[80:83], v[8:11]
	v_mfma_f32_16x16x32_bf16 v[12:15], v[124:127], v[80:83], v[12:15]
	v_mfma_f32_16x16x32_bf16 v[16:19], v[112:115], v[84:87], v[16:19]
	v_mfma_f32_16x16x32_bf16 v[20:23], v[116:119], v[84:87], v[20:23]
	v_mfma_f32_16x16x32_bf16 v[24:27], v[120:123], v[84:87], v[24:27]
	v_mfma_f32_16x16x32_bf16 v[28:31], v[124:127], v[84:87], v[28:31]
	v_mfma_f32_16x16x32_bf16 v[32:35], v[112:115], v[88:91], v[32:35]
	v_mfma_f32_16x16x32_bf16 v[36:39], v[116:119], v[88:91], v[36:39]
	v_mfma_f32_16x16x32_bf16 v[40:43], v[120:123], v[88:91], v[40:43]
	v_mfma_f32_16x16x32_bf16 v[44:47], v[124:127], v[88:91], v[44:47]
	v_mfma_f32_16x16x32_bf16 v[48:51], v[112:115], v[92:95], v[48:51]
	v_mfma_f32_16x16x32_bf16 v[52:55], v[116:119], v[92:95], v[52:55]
	v_mfma_f32_16x16x32_bf16 v[56:59], v[120:123], v[92:95], v[56:59]
	v_mfma_f32_16x16x32_bf16 v[60:63], v[124:127], v[92:95], v[60:63]
	ds_read_b128 v[80:83], v253 offset:0
	ds_read_b128 v[112:115], v255 offset:32768
	ds_read_b128 v[116:119], v255 offset:34816
	ds_read_b128 v[120:123], v255 offset:36864
	ds_read_b128 v[124:127], v255 offset:38912
	ds_read_b128 v[84:87], v253 offset:2048
	ds_read_b128 v[88:91], v253 offset:4096
	ds_read_b128 v[92:95], v253 offset:6144
	s_waitcnt lgkmcnt(14)
	v_mfma_f32_16x16x32_bf16 v[0:3], v[96:99], v[64:67], v[0:3]
	s_waitcnt lgkmcnt(13)
	v_mfma_f32_16x16x32_bf16 v[4:7], v[100:103], v[64:67], v[4:7]
	s_waitcnt lgkmcnt(12)
	v_mfma_f32_16x16x32_bf16 v[8:11], v[104:107], v[64:67], v[8:11]
	s_waitcnt lgkmcnt(11)
	v_mfma_f32_16x16x32_bf16 v[12:15], v[108:111], v[64:67], v[12:15]
	s_waitcnt lgkmcnt(10)
	v_mfma_f32_16x16x32_bf16 v[16:19], v[96:99], v[68:71], v[16:19]
	v_mfma_f32_16x16x32_bf16 v[20:23], v[100:103], v[68:71], v[20:23]
	v_mfma_f32_16x16x32_bf16 v[24:27], v[104:107], v[68:71], v[24:27]
	v_mfma_f32_16x16x32_bf16 v[28:31], v[108:111], v[68:71], v[28:31]
	s_waitcnt lgkmcnt(0)
	s_barrier
	s_add_u32 m0, s12, 0x0
	v_mfma_f32_16x16x32_bf16 v[32:35], v[96:99], v[72:75], v[32:35]
	global_load_lds_dwordx4 v248, s[8:9]
	s_add_u32 m0, s12, 0x400
	v_mfma_f32_16x16x32_bf16 v[36:39], v[100:103], v[72:75], v[36:39]
	global_load_lds_dwordx4 v249, s[8:9]
	s_add_u32 m0, s12, 0x800
	v_mfma_f32_16x16x32_bf16 v[40:43], v[104:107], v[72:75], v[40:43]
	global_load_lds_dwordx4 v250, s[8:9]
	s_add_u32 m0, s12, 0xc00
	v_mfma_f32_16x16x32_bf16 v[44:47], v[108:111], v[72:75], v[44:47]
	global_load_lds_dwordx4 v251, s[8:9]
	s_add_u32 m0, s12, 0x8000
	v_mfma_f32_16x16x32_bf16 v[48:51], v[96:99], v[76:79], v[48:51]
	global_load_lds_dwordx4 v248, s[10:11] sc1
	s_add_u32 m0, s12, 0x8400
	v_mfma_f32_16x16x32_bf16 v[52:55], v[100:103], v[76:79], v[52:55]
	global_load_lds_dwordx4 v249, s[10:11] sc1
	s_add_u32 m0, s12, 0x8800
	v_mfma_f32_16x16x32_bf16 v[56:59], v[104:107], v[76:79], v[56:59]
	global_load_lds_dwordx4 v250, s[10:11] sc1
	s_add_u32 m0, s12, 0x8c00
	v_mfma_f32_16x16x32_bf16 v[60:63], v[108:111], v[76:79], v[60:63]
	global_load_lds_dwordx4 v251, s[10:11] sc1
	s_sub_u32 s23, s23, 1
	s_cmp_eq_u32 s23, 0
	s_cselect_b32 s14, 0x800, 0
	s_sub_u32 s8, s8, s14
	s_subb_u32 s9, s9, 0
	s_add_u32 s8, s8, 0x80
	s_addc_u32 s9, s9, 0
	s_sub_u32 s10, s10, s14
	s_subb_u32 s11, s11, 0
	s_add_u32 s10, s10, 0x80
	s_addc_u32 s11, s11, 0
	s_waitcnt vmcnt(8)
	s_barrier
	ds_read_b128 v[64:67], v252 offset:16384
	ds_read_b128 v[96:99], v254 offset:49152
	ds_read_b128 v[100:103], v254 offset:51200
	ds_read_b128 v[104:107], v254 offset:53248
	ds_read_b128 v[108:111], v254 offset:55296
	ds_read_b128 v[68:71], v252 offset:18432
	ds_read_b128 v[72:75], v252 offset:20480
	ds_read_b128 v[76:79], v252 offset:22528
	v_mfma_f32_16x16x32_bf16 v[0:3], v[112:115], v[80:83], v[0:3]
	v_mfma_f32_16x16x32_bf16 v[4:7], v[116:119], v[80:83], v[4:7]
	v_mfma_f32_16x16x32_bf16 v[8:11], v[120:123], v[80:83], v[8:11]
	v_mfma_f32_16x16x32_bf16 v[12:15], v[124:127], v[80:83], v[12:15]
	v_mfma_f32_16x16x32_bf16 v[16:19], v[112:115], v[84:87], v[16:19]
	v_mfma_f32_16x16x32_bf16 v[20:23], v[116:119], v[84:87], v[20:23]
	v_mfma_f32_16x16x32_bf16 v[24:27], v[120:123], v[84:87], v[24:27]
	v_mfma_f32_16x16x32_bf16 v[28:31], v[124:127], v[84:87], v[28:31]
	v_mfma_f32_16x16x32_bf16 v[32:35], v[112:115], v[88:91], v[32:35]
	v_mfma_f32_16x16x32_bf16 v[36:39], v[116:119], v[88:91], v[36:39]
	v_mfma_f32_16x16x32_bf16 v[40:43], v[120:123], v[88:91], v[40:43]
	v_mfma_f32_16x16x32_bf16 v[44:47], v[124:127], v[88:91], v[44:47]
	v_mfma_f32_16x16x32_bf16 v[48:51], v[112:115], v[92:95], v[48:51]
	v_mfma_f32_16x16x32_bf16 v[52:55], v[116:119], v[92:95], v[52:55]
	v_mfma_f32_16x16x32_bf16 v[56:59], v[120:123], v[92:95], v[56:59]
	v_mfma_f32_16x16x32_bf16 v[60:63], v[124:127], v[92:95], v[60:63]
	ds_read_b128 v[80:83], v253 offset:16384
	ds_read_b128 v[112:115], v255 offset:49152
	ds_read_b128 v[116:119], v255 offset:51200
	ds_read_b128 v[120:123], v255 offset:53248
	ds_read_b128 v[124:127], v255 offset:55296
	ds_read_b128 v[84:87], v253 offset:18432
	ds_read_b128 v[88:91], v253 offset:20480
	ds_read_b128 v[92:95], v253 offset:22528
	s_waitcnt lgkmcnt(14)
	v_mfma_f32_16x16x32_bf16 v[0:3], v[96:99], v[64:67], v[0:3]
	s_waitcnt lgkmcnt(13)
	v_mfma_f32_16x16x32_bf16 v[4:7], v[100:103], v[64:67], v[4:7]
	s_waitcnt lgkmcnt(12)
	v_mfma_f32_16x16x32_bf16 v[8:11], v[104:107], v[64:67], v[8:11]
	s_waitcnt lgkmcnt(11)
	v_mfma_f32_16x16x32_bf16 v[12:15], v[108:111], v[64:67], v[12:15]
	s_waitcnt lgkmcnt(10)
	v_mfma_f32_16x16x32_bf16 v[16:19], v[96:99], v[68:71], v[16:19]
	v_mfma_f32_16x16x32_bf16 v[20:23], v[100:103], v[68:71], v[20:23]
	v_mfma_f32_16x16x32_bf16 v[24:27], v[104:107], v[68:71], v[24:27]
	v_mfma_f32_16x16x32_bf16 v[28:31], v[108:111], v[68:71], v[28:31]
	s_waitcnt lgkmcnt(0)
	s_barrier
	s_add_u32 m0, s12, 0x4000
	v_mfma_f32_16x16x32_bf16 v[32:35], v[96:99], v[72:75], v[32:35]
	global_load_lds_dwordx4 v248, s[8:9]
	s_add_u32 m0, s12, 0x4400
	v_mfma_f32_16x16x32_bf16 v[36:39], v[100:103], v[72:75], v[36:39]
	global_load_lds_dwordx4 v249, s[8:9]
	s_add_u32 m0, s12, 0x4800
	v_mfma_f32_16x16x32_bf16 v[40:43], v[104:107], v[72:75], v[40:43]
	global_load_lds_dwordx4 v250, s[8:9]
	s_add_u32 m0, s12, 0x4c00
	v_mfma_f32_16x16x32_bf16 v[44:47], v[108:111], v[72:75], v[44:47]
	global_load_lds_dwordx4 v251, s[8:9]
	s_add_u32 m0, s12, 0xc000
	v_mfma_f32_16x16x32_bf16 v[48:51], v[96:99], v[76:79], v[48:51]
	global_load_lds_dwordx4 v248, s[10:11] sc1
	s_add_u32 m0, s12, 0xc400
	v_mfma_f32_16x16x32_bf16 v[52:55], v[100:103], v[76:79], v[52:55]
	global_load_lds_dwordx4 v249, s[10:11] sc1
	s_add_u32 m0, s12, 0xc800
	v_mfma_f32_16x16x32_bf16 v[56:59], v[104:107], v[76:79], v[56:59]
	global_load_lds_dwordx4 v250, s[10:11] sc1
	s_add_u32 m0, s12, 0xcc00
	v_mfma_f32_16x16x32_bf16 v[60:63], v[108:111], v[76:79], v[60:63]
	global_load_lds_dwordx4 v251, s[10:11] sc1
	s_sub_u32 s23, s23, 1
	s_cmp_eq_u32 s23, 0
	s_cselect_b32 s14, 0x800, 0
	s_sub_u32 s8, s8, s14
	s_subb_u32 s9, s9, 0
	s_add_u32 s8, s8, 0x80
	s_addc_u32 s9, s9, 0
	s_sub_u32 s10, s10, s14
	s_subb_u32 s11, s11, 0
	s_add_u32 s10, s10, 0x80
	s_addc_u32 s11, s11, 0
	s_sub_u32 s13, s13, 1
	s_cmp_lg_u32 s13, 0
	s_cbranch_scc1 .Lf8_loop
	s_waitcnt vmcnt(8)
	s_barrier
	ds_read_b128 v[64:67], v252 offset:0
	ds_read_b128 v[96:99], v254 offset:32768
	ds_read_b128 v[100:103], v254 offset:34816
	ds_read_b128 v[104:107], v254 offset:36864
	ds_read_b128 v[108:111], v254 offset:38912
	ds_read_b128 v[68:71], v252 offset:2048
	ds_read_b128 v[72:75], v252 offset:4096
	ds_read_b128 v[76:79], v252 offset:6144
	v_mfma_f32_16x16x32_bf16 v[0:3], v[112:115], v[80:83], v[0:3]
	v_mfma_f32_16x16x32_bf16 v[4:7], v[116:119], v[80:83], v[4:7]
	v_mfma_f32_16x16x32_bf16 v[8:11], v[120:123], v[80:83], v[8:11]
	v_mfma_f32_16x16x32_bf16 v[12:15], v[124:127], v[80:83], v[12:15]
	v_mfma_f32_16x16x32_bf16 v[16:19], v[112:115], v[84:87], v[16:19]
	v_mfma_f32_16x16x32_bf16 v[20:23], v[116:119], v[84:87], v[20:23]
	v_mfma_f32_16x16x32_bf16 v[24:27], v[120:123], v[84:87], v[24:27]
	v_mfma_f32_16x16x32_bf16 v[28:31], v[124:127], v[84:87], v[28:31]
	v_mfma_f32_16x16x32_bf16 v[32:35], v[112:115], v[88:91], v[32:35]
	v_mfma_f32_16x16x32_bf16 v[36:39], v[116:119], v[88:91], v[36:39]
	v_mfma_f32_16x16x32_bf16 v[40:43], v[120:123], v[88:91], v[40:43]
	v_mfma_f32_16x16x32_bf16 v[44:47], v[124:127], v[88:91], v[44:47]
	v_mfma_f32_16x16x32_bf16 v[48:51], v[112:115], v[92:95], v[48:51]
	v_mfma_f32_16x16x32_bf16 v[52:55], v[116:119], v[92:95], v[52:55]
	v_mfma_f32_16x16x32_bf16 v[56:59], v[120:123], v[92:95], v[56:59]
	v_mfma_f32_16x16x32_bf16 v[60:63], v[124:127], v[92:95], v[60:63]
	ds_read_b128 v[80:83], v253 offset:0
	ds_read_b128 v[112:115], v255 offset:32768
	ds_read_b128 v[116:119], v255 offset:34816
	ds_read_b128 v[120:123], v255 offset:36864
	ds_read_b128 v[124:127], v255 offset:38912
	ds_read_b128 v[84:87], v253 offset:2048
	ds_read_b128 v[88:91], v253 offset:4096
	ds_read_b128 v[92:95], v253 offset:6144
	s_waitcnt lgkmcnt(14)
	v_mfma_f32_16x16x32_bf16 v[0:3], v[96:99], v[64:67], v[0:3]
	s_waitcnt lgkmcnt(13)
	v_mfma_f32_16x16x32_bf16 v[4:7], v[100:103], v[64:67], v[4:7]
	s_waitcnt lgkmcnt(12)
	v_mfma_f32_16x16x32_bf16 v[8:11], v[104:107], v[64:67], v[8:11]
	s_waitcnt lgkmcnt(11)
	v_mfma_f32_16x16x32_bf16 v[12:15], v[108:111], v[64:67], v[12:15]
	s_waitcnt lgkmcnt(10)
	v_mfma_f32_16x16x32_bf16 v[16:19], v[96:99], v[68:71], v[16:19]
	v_mfma_f32_16x16x32_bf16 v[20:23], v[100:103], v[68:71], v[20:23]
	v_mfma_f32_16x16x32_bf16 v[24:27], v[104:107], v[68:71], v[24:27]
	v_mfma_f32_16x16x32_bf16 v[28:31], v[108:111], v[68:71], v[28:31]
	s_waitcnt lgkmcnt(0)
	s_barrier
	v_mfma_f32_16x16x32_bf16 v[32:35], v[96:99], v[72:75], v[32:35]
	v_mfma_f32_16x16x32_bf16 v[36:39], v[100:103], v[72:75], v[36:39]
	v_mfma_f32_16x16x32_bf16 v[40:43], v[104:107], v[72:75], v[40:43]
	v_mfma_f32_16x16x32_bf16 v[44:47], v[108:111], v[72:75], v[44:47]
	v_mfma_f32_16x16x32_bf16 v[48:51], v[96:99], v[76:79], v[48:51]
	v_mfma_f32_16x16x32_bf16 v[52:55], v[100:103], v[76:79], v[52:55]
	v_mfma_f32_16x16x32_bf16 v[56:59], v[104:107], v[76:79], v[56:59]
	v_mfma_f32_16x16x32_bf16 v[60:63], v[108:111], v[76:79], v[60:63]
	s_waitcnt vmcnt(0)
	s_barrier
	ds_read_b128 v[64:67], v252 offset:16384
	ds_read_b128 v[96:99], v254 offset:49152
	ds_read_b128 v[100:103], v254 offset:51200
	ds_read_b128 v[104:107], v254 offset:53248
	ds_read_b128 v[108:111], v254 offset:55296
	ds_read_b128 v[68:71], v252 offset:18432
	ds_read_b128 v[72:75], v252 offset:20480
	ds_read_b128 v[76:79], v252 offset:22528
	v_mfma_f32_16x16x32_bf16 v[0:3], v[112:115], v[80:83], v[0:3]
	v_mfma_f32_16x16x32_bf16 v[4:7], v[116:119], v[80:83], v[4:7]
	v_mfma_f32_16x16x32_bf16 v[8:11], v[120:123], v[80:83], v[8:11]
	v_mfma_f32_16x16x32_bf16 v[12:15], v[124:127], v[80:83], v[12:15]
	v_mfma_f32_16x16x32_bf16 v[16:19], v[112:115], v[84:87], v[16:19]
	v_mfma_f32_16x16x32_bf16 v[20:23], v[116:119], v[84:87], v[20:23]
	v_mfma_f32_16x16x32_bf16 v[24:27], v[120:123], v[84:87], v[24:27]
	v_mfma_f32_16x16x32_bf16 v[28:31], v[124:127], v[84:87], v[28:31]
	v_mfma_f32_16x16x32_bf16 v[32:35], v[112:115], v[88:91], v[32:35]
	v_mfma_f32_16x16x32_bf16 v[36:39], v[116:119], v[88:91], v[36:39]
	v_mfma_f32_16x16x32_bf16 v[40:43], v[120:123], v[88:91], v[40:43]
	v_mfma_f32_16x16x32_bf16 v[44:47], v[124:127], v[88:91], v[44:47]
	v_mfma_f32_16x16x32_bf16 v[48:51], v[112:115], v[92:95], v[48:51]
	v_mfma_f32_16x16x32_bf16 v[52:55], v[116:119], v[92:95], v[52:55]
	v_mfma_f32_16x16x32_bf16 v[56:59], v[120:123], v[92:95], v[56:59]
	v_mfma_f32_16x16x32_bf16 v[60:63], v[124:127], v[92:95], v[60:63]
	ds_read_b128 v[80:83], v253 offset:16384
	ds_read_b128 v[112:115], v255 offset:49152
	ds_read_b128 v[116:119], v255 offset:51200
	ds_read_b128 v[120:123], v255 offset:53248
	ds_read_b128 v[124:127], v255 offset:55296
	ds_read_b128 v[84:87], v253 offset:18432
	ds_read_b128 v[88:91], v253 offset:20480
	ds_read_b128 v[92:95], v253 offset:22528
	s_waitcnt lgkmcnt(14)
	v_mfma_f32_16x16x32_bf16 v[0:3], v[96:99], v[64:67], v[0:3]
	s_waitcnt lgkmcnt(13)
	v_mfma_f32_16x16x32_bf16 v[4:7], v[100:103], v[64:67], v[4:7]
	s_waitcnt lgkmcnt(12)
	v_mfma_f32_16x16x32_bf16 v[8:11], v[104:107], v[64:67], v[8:11]
	s_waitcnt lgkmcnt(11)
	v_mfma_f32_16x16x32_bf16 v[12:15], v[108:111], v[64:67], v[12:15]
	s_waitcnt lgkmcnt(10)
	v_mfma_f32_16x16x32_bf16 v[16:19], v[96:99], v[68:71], v[16:19]
	v_mfma_f32_16x16x32_bf16 v[20:23], v[100:103], v[68:71], v[20:23]
	v_mfma_f32_16x16x32_bf16 v[24:27], v[104:107], v[68:71], v[24:27]
	v_mfma_f32_16x16x32_bf16 v[28:31], v[108:111], v[68:71], v[28:31]
	s_waitcnt lgkmcnt(0)
	s_barrier
	v_mfma_f32_16x16x32_bf16 v[32:35], v[96:99], v[72:75], v[32:35]
	v_mfma_f32_16x16x32_bf16 v[36:39], v[100:103], v[72:75], v[36:39]
	v_mfma_f32_16x16x32_bf16 v[40:43], v[104:107], v[72:75], v[40:43]
	v_mfma_f32_16x16x32_bf16 v[44:47], v[108:111], v[72:75], v[44:47]
	v_mfma_f32_16x16x32_bf16 v[48:51], v[96:99], v[76:79], v[48:51]
	v_mfma_f32_16x16x32_bf16 v[52:55], v[100:103], v[76:79], v[52:55]
	v_mfma_f32_16x16x32_bf16 v[56:59], v[104:107], v[76:79], v[56:59]
	v_mfma_f32_16x16x32_bf16 v[60:63], v[108:111], v[76:79], v[60:63]
	v_mfma_f32_16x16x32_bf16 v[0:3], v[112:115], v[80:83], v[0:3]
	v_mfma_f32_16x16x32_bf16 v[4:7], v[116:119], v[80:83], v[4:7]
	v_mfma_f32_16x16x32_bf16 v[8:11], v[120:123], v[80:83], v[8:11]
	v_mfma_f32_16x16x32_bf16 v[12:15], v[124:127], v[80:83], v[12:15]
	v_mfma_f32_16x16x32_bf16 v[16:19], v[112:115], v[84:87], v[16:19]
	v_mfma_f32_16x16x32_bf16 v[20:23], v[116:119], v[84:87], v[20:23]
	v_mfma_f32_16x16x32_bf16 v[24:27], v[120:123], v[84:87], v[24:27]
	v_mfma_f32_16x16x32_bf16 v[28:31], v[124:127], v[84:87], v[28:31]
	v_mfma_f32_16x16x32_bf16 v[32:35], v[112:115], v[88:91], v[32:35]
	v_mfma_f32_16x16x32_bf16 v[36:39], v[116:119], v[88:91], v[36:39]
	v_mfma_f32_16x16x32_bf16 v[40:43], v[120:123], v[88:91], v[40:43]
	v_mfma_f32_16x16x32_bf16 v[44:47], v[124:127], v[88:91], v[44:47]
	v_mfma_f32_16x16x32_bf16 v[48:51], v[112:115], v[92:95], v[48:51]
	v_mfma_f32_16x16x32_bf16 v[52:55], v[116:119], v[92:95], v[52:55]
	v_mfma_f32_16x16x32_bf16 v[56:59], v[120:123], v[92:95], v[56:59]
	v_mfma_f32_16x16x32_bf16 v[60:63], v[124:127], v[92:95], v[60:63]
	s_nop 7
	s_nop 1
	v_mul_f32_e32 v130, 0xbfb8aa3b, v0
	v_mul_f32_e32 v131, 0xbfb8aa3b, v1
	v_mul_f32_e32 v132, 0xbfb8aa3b, v2
	v_mul_f32_e32 v133, 0xbfb8aa3b, v3
	v_mul_f32_e32 v134, 0xbfb8aa3b, v4
	v_mul_f32_e32 v135, 0xbfb8aa3b, v5
	v_mul_f32_e32 v136, 0xbfb8aa3b, v6
	v_mul_f32_e32 v137, 0xbfb8aa3b, v7
	v_exp_f32_e32 v130, v130
	v_exp_f32_e32 v131, v131
	v_exp_f32_e32 v132, v132
	v_exp_f32_e32 v133, v133
	v_exp_f32_e32 v134, v134
	v_exp_f32_e32 v135, v135
	v_exp_f32_e32 v136, v136
	v_exp_f32_e32 v137, v137
	v_add_f32_e32 v130, 1.0, v130
	v_add_f32_e32 v131, 1.0, v131
	v_add_f32_e32 v132, 1.0, v132
	v_add_f32_e32 v133, 1.0, v133
	v_add_f32_e32 v134, 1.0, v134
	v_add_f32_e32 v135, 1.0, v135
	v_add_f32_e32 v136, 1.0, v136
	v_add_f32_e32 v137, 1.0, v137
	v_rcp_f32_e32 v130, v130
	v_rcp_f32_e32 v131, v131
	v_rcp_f32_e32 v132, v132
	v_rcp_f32_e32 v133, v133
	v_rcp_f32_e32 v134, v134
	v_rcp_f32_e32 v135, v135
	v_rcp_f32_e32 v136, v136
	v_rcp_f32_e32 v137, v137
	v_mul_f32_e32 v130, v0, v130
	v_mul_f32_e32 v131, v1, v131
	v_mul_f32_e32 v132, v2, v132
	v_mul_f32_e32 v133, v3, v133
	v_mul_f32_e32 v134, v4, v134
	v_mul_f32_e32 v135, v5, v135
	v_mul_f32_e32 v136, v6, v136
	v_mul_f32_e32 v137, v7, v137
	v_mul_f32_e32 v130, v8, v130
	v_mul_f32_e32 v131, v9, v131
	v_mul_f32_e32 v132, v10, v132
	v_mul_f32_e32 v133, v11, v133
	v_mul_f32_e32 v134, v12, v134
	v_mul_f32_e32 v135, v13, v135
	v_mul_f32_e32 v136, v14, v136
	v_mul_f32_e32 v137, v15, v137
	v_cvt_pk_bf16_f32 v0, v130, v131
	v_cvt_pk_bf16_f32 v1, v132, v133
	v_cvt_pk_bf16_f32 v2, v134, v135
	v_cvt_pk_bf16_f32 v3, v136, v137
	ds_write_b64 v245, v[0:1] offset:0
	ds_write_b64 v245, v[2:3] offset:32
	v_mul_f32_e32 v130, 0xbfb8aa3b, v16
	v_mul_f32_e32 v131, 0xbfb8aa3b, v17
	v_mul_f32_e32 v132, 0xbfb8aa3b, v18
	v_mul_f32_e32 v133, 0xbfb8aa3b, v19
	v_mul_f32_e32 v134, 0xbfb8aa3b, v20
	v_mul_f32_e32 v135, 0xbfb8aa3b, v21
	v_mul_f32_e32 v136, 0xbfb8aa3b, v22
	v_mul_f32_e32 v137, 0xbfb8aa3b, v23
	v_exp_f32_e32 v130, v130
	v_exp_f32_e32 v131, v131
	v_exp_f32_e32 v132, v132
	v_exp_f32_e32 v133, v133
	v_exp_f32_e32 v134, v134
	v_exp_f32_e32 v135, v135
	v_exp_f32_e32 v136, v136
	v_exp_f32_e32 v137, v137
	v_add_f32_e32 v130, 1.0, v130
	v_add_f32_e32 v131, 1.0, v131
	v_add_f32_e32 v132, 1.0, v132
	v_add_f32_e32 v133, 1.0, v133
	v_add_f32_e32 v134, 1.0, v134
	v_add_f32_e32 v135, 1.0, v135
	v_add_f32_e32 v136, 1.0, v136
	v_add_f32_e32 v137, 1.0, v137
	v_rcp_f32_e32 v130, v130
	v_rcp_f32_e32 v131, v131
	v_rcp_f32_e32 v132, v132
	v_rcp_f32_e32 v133, v133
	v_rcp_f32_e32 v134, v134
	v_rcp_f32_e32 v135, v135
	v_rcp_f32_e32 v136, v136
	v_rcp_f32_e32 v137, v137
	v_mul_f32_e32 v130, v16, v130
	v_mul_f32_e32 v131, v17, v131
	v_mul_f32_e32 v132, v18, v132
	v_mul_f32_e32 v133, v19, v133
	v_mul_f32_e32 v134, v20, v134
	v_mul_f32_e32 v135, v21, v135
	v_mul_f32_e32 v136, v22, v136
	v_mul_f32_e32 v137, v23, v137
	v_mul_f32_e32 v130, v24, v130
	v_mul_f32_e32 v131, v25, v131
	v_mul_f32_e32 v132, v26, v132
	v_mul_f32_e32 v133, v27, v133
	v_mul_f32_e32 v134, v28, v134
	v_mul_f32_e32 v135, v29, v135
	v_mul_f32_e32 v136, v30, v136
	v_mul_f32_e32 v137, v31, v137
	v_cvt_pk_bf16_f32 v16, v130, v131
	v_cvt_pk_bf16_f32 v17, v132, v133
	v_cvt_pk_bf16_f32 v18, v134, v135
	v_cvt_pk_bf16_f32 v19, v136, v137
	ds_write_b64 v245, v[16:17] offset:1280
	ds_write_b64 v245, v[18:19] offset:1312
	v_mul_f32_e32 v130, 0xbfb8aa3b, v32
	v_mul_f32_e32 v131, 0xbfb8aa3b, v33
	v_mul_f32_e32 v132, 0xbfb8aa3b, v34
	v_mul_f32_e32 v133, 0xbfb8aa3b, v35
	v_mul_f32_e32 v134, 0xbfb8aa3b, v36
	v_mul_f32_e32 v135, 0xbfb8aa3b, v37
	v_mul_f32_e32 v136, 0xbfb8aa3b, v38
	v_mul_f32_e32 v137, 0xbfb8aa3b, v39
	v_exp_f32_e32 v130, v130
	v_exp_f32_e32 v131, v131
	v_exp_f32_e32 v132, v132
	v_exp_f32_e32 v133, v133
	v_exp_f32_e32 v134, v134
	v_exp_f32_e32 v135, v135
	v_exp_f32_e32 v136, v136
	v_exp_f32_e32 v137, v137
	v_add_f32_e32 v130, 1.0, v130
	v_add_f32_e32 v131, 1.0, v131
	v_add_f32_e32 v132, 1.0, v132
	v_add_f32_e32 v133, 1.0, v133
	v_add_f32_e32 v134, 1.0, v134
	v_add_f32_e32 v135, 1.0, v135
	v_add_f32_e32 v136, 1.0, v136
	v_add_f32_e32 v137, 1.0, v137
	v_rcp_f32_e32 v130, v130
	v_rcp_f32_e32 v131, v131
	v_rcp_f32_e32 v132, v132
	v_rcp_f32_e32 v133, v133
	v_rcp_f32_e32 v134, v134
	v_rcp_f32_e32 v135, v135
	v_rcp_f32_e32 v136, v136
	v_rcp_f32_e32 v137, v137
	v_mul_f32_e32 v130, v32, v130
	v_mul_f32_e32 v131, v33, v131
	v_mul_f32_e32 v132, v34, v132
	v_mul_f32_e32 v133, v35, v133
	v_mul_f32_e32 v134, v36, v134
	v_mul_f32_e32 v135, v37, v135
	v_mul_f32_e32 v136, v38, v136
	v_mul_f32_e32 v137, v39, v137
	v_mul_f32_e32 v130, v40, v130
	v_mul_f32_e32 v131, v41, v131
	v_mul_f32_e32 v132, v42, v132
	v_mul_f32_e32 v133, v43, v133
	v_mul_f32_e32 v134, v44, v134
	v_mul_f32_e32 v135, v45, v135
	v_mul_f32_e32 v136, v46, v136
	v_mul_f32_e32 v137, v47, v137
	v_cvt_pk_bf16_f32 v32, v130, v131
	v_cvt_pk_bf16_f32 v33, v132, v133
	v_cvt_pk_bf16_f32 v34, v134, v135
	v_cvt_pk_bf16_f32 v35, v136, v137
	ds_write_b64 v245, v[32:33] offset:2560
	ds_write_b64 v245, v[34:35] offset:2592
	v_mul_f32_e32 v130, 0xbfb8aa3b, v48
	v_mul_f32_e32 v131, 0xbfb8aa3b, v49
	v_mul_f32_e32 v132, 0xbfb8aa3b, v50
	v_mul_f32_e32 v133, 0xbfb8aa3b, v51
	v_mul_f32_e32 v134, 0xbfb8aa3b, v52
	v_mul_f32_e32 v135, 0xbfb8aa3b, v53
	v_mul_f32_e32 v136, 0xbfb8aa3b, v54
	v_mul_f32_e32 v137, 0xbfb8aa3b, v55
	v_exp_f32_e32 v130, v130
	v_exp_f32_e32 v131, v131
	v_exp_f32_e32 v132, v132
	v_exp_f32_e32 v133, v133
	v_exp_f32_e32 v134, v134
	v_exp_f32_e32 v135, v135
	v_exp_f32_e32 v136, v136
	v_exp_f32_e32 v137, v137
	v_add_f32_e32 v130, 1.0, v130
	v_add_f32_e32 v131, 1.0, v131
	v_add_f32_e32 v132, 1.0, v132
	v_add_f32_e32 v133, 1.0, v133
	v_add_f32_e32 v134, 1.0, v134
	v_add_f32_e32 v135, 1.0, v135
	v_add_f32_e32 v136, 1.0, v136
	v_add_f32_e32 v137, 1.0, v137
	v_rcp_f32_e32 v130, v130
	v_rcp_f32_e32 v131, v131
	v_rcp_f32_e32 v132, v132
	v_rcp_f32_e32 v133, v133
	v_rcp_f32_e32 v134, v134
	v_rcp_f32_e32 v135, v135
	v_rcp_f32_e32 v136, v136
	v_rcp_f32_e32 v137, v137
	v_mul_f32_e32 v130, v48, v130
	v_mul_f32_e32 v131, v49, v131
	v_mul_f32_e32 v132, v50, v132
	v_mul_f32_e32 v133, v51, v133
	v_mul_f32_e32 v134, v52, v134
	v_mul_f32_e32 v135, v53, v135
	v_mul_f32_e32 v136, v54, v136
	v_mul_f32_e32 v137, v55, v137
	v_mul_f32_e32 v130, v56, v130
	v_mul_f32_e32 v131, v57, v131
	v_mul_f32_e32 v132, v58, v132
	v_mul_f32_e32 v133, v59, v133
	v_mul_f32_e32 v134, v60, v134
	v_mul_f32_e32 v135, v61, v135
	v_mul_f32_e32 v136, v62, v136
	v_mul_f32_e32 v137, v63, v137
	v_cvt_pk_bf16_f32 v48, v130, v131
	v_cvt_pk_bf16_f32 v49, v132, v133
	v_cvt_pk_bf16_f32 v50, v134, v135
	v_cvt_pk_bf16_f32 v51, v136, v137
	ds_write_b64 v245, v[48:49] offset:3840
	ds_write_b64 v245, v[50:51] offset:3872
	s_waitcnt lgkmcnt(0)
	ds_read_b128 v[138:141], v246 offset:0
	ds_read_b128 v[142:145], v246 offset:1280
	ds_read_b128 v[146:149], v246 offset:2560
	ds_read_b128 v[150:153], v246 offset:3840
	s_mov_b64 s[18:19], s[20:21]
	s_waitcnt lgkmcnt(3)
	global_store_dwordx4 v239, v[138:141], s[18:19]
	s_add_u32 s18, s18, 0x16000
	s_addc_u32 s19, s19, 0
	s_waitcnt lgkmcnt(2)
	global_store_dwordx4 v239, v[142:145], s[18:19]
	s_add_u32 s18, s18, 0x16000
	s_addc_u32 s19, s19, 0
	s_waitcnt lgkmcnt(1)
	global_store_dwordx4 v239, v[146:149], s[18:19]
	s_add_u32 s18, s18, 0x16000
	s_addc_u32 s19, s19, 0
	s_waitcnt lgkmcnt(0)
	global_store_dwordx4 v239, v[150:153], s[18:19]
	s_barrier
	s_add_u32 s15, s15, s16
	s_branch .Lf8_tile

.Lr13_loop:
	s_waitcnt vmcnt(8)
	s_barrier
	ds_read_b128 v[64:67], v252 offset:0
	ds_read_b128 v[96:99], v254 offset:32768
	ds_read_b128 v[100:103], v254 offset:34816
	ds_read_b128 v[104:107], v254 offset:36864
	ds_read_b128 v[108:111], v254 offset:38912
	ds_read_b128 v[68:71], v252 offset:2048
	ds_read_b128 v[72:75], v252 offset:4096
	ds_read_b128 v[76:79], v252 offset:6144
	v_mfma_f32_16x16x32_bf16 v[0:3], v[80:83], v[112:115], v[0:3]
	v_mfma_f32_16x16x32_bf16 v[4:7], v[80:83], v[116:119], v[4:7]
	v_mfma_f32_16x16x32_bf16 v[8:11], v[80:83], v[120:123], v[8:11]
	v_mfma_f32_16x16x32_bf16 v[12:15], v[80:83], v[124:127], v[12:15]
	v_mfma_f32_16x16x32_bf16 v[16:19], v[84:87], v[112:115], v[16:19]
	v_mfma_f32_16x16x32_bf16 v[20:23], v[84:87], v[116:119], v[20:23]
	v_mfma_f32_16x16x32_bf16 v[24:27], v[84:87], v[120:123], v[24:27]
	v_mfma_f32_16x16x32_bf16 v[28:31], v[84:87], v[124:127], v[28:31]
	v_mfma_f32_16x16x32_bf16 v[32:35], v[88:91], v[112:115], v[32:35]
	v_mfma_f32_16x16x32_bf16 v[36:39], v[88:91], v[116:119], v[36:39]
	v_mfma_f32_16x16x32_bf16 v[40:43], v[88:91], v[120:123], v[40:43]
	v_mfma_f32_16x16x32_bf16 v[44:47], v[88:91], v[124:127], v[44:47]
	v_mfma_f32_16x16x32_bf16 v[48:51], v[92:95], v[112:115], v[48:51]
	v_mfma_f32_16x16x32_bf16 v[52:55], v[92:95], v[116:119], v[52:55]
	v_mfma_f32_16x16x32_bf16 v[56:59], v[92:95], v[120:123], v[56:59]
	v_mfma_f32_16x16x32_bf16 v[60:63], v[92:95], v[124:127], v[60:63]
	ds_read_b128 v[80:83], v253 offset:0
	ds_read_b128 v[112:115], v255 offset:32768
	ds_read_b128 v[116:119], v255 offset:34816
	ds_read_b128 v[120:123], v255 offset:36864
	ds_read_b128 v[124:127], v255 offset:38912
	ds_read_b128 v[84:87], v253 offset:2048
	ds_read_b128 v[88:91], v253 offset:4096
	ds_read_b128 v[92:95], v253 offset:6144
	s_waitcnt lgkmcnt(14)
	v_mfma_f32_16x16x32_bf16 v[0:3], v[64:67], v[96:99], v[0:3]
	s_waitcnt lgkmcnt(13)
	v_mfma_f32_16x16x32_bf16 v[4:7], v[64:67], v[100:103], v[4:7]
	s_waitcnt lgkmcnt(12)
	v_mfma_f32_16x16x32_bf16 v[8:11], v[64:67], v[104:107], v[8:11]
	s_waitcnt lgkmcnt(11)
	v_mfma_f32_16x16x32_bf16 v[12:15], v[64:67], v[108:111], v[12:15]
	s_waitcnt lgkmcnt(10)
	v_mfma_f32_16x16x32_bf16 v[16:19], v[68:71], v[96:99], v[16:19]
	v_mfma_f32_16x16x32_bf16 v[20:23], v[68:71], v[100:103], v[20:23]
	v_mfma_f32_16x16x32_bf16 v[24:27], v[68:71], v[104:107], v[24:27]
	v_mfma_f32_16x16x32_bf16 v[28:31], v[68:71], v[108:111], v[28:31]
	s_waitcnt lgkmcnt(0)
	s_barrier
	s_add_u32 m0, s12, 0x0
	v_mfma_f32_16x16x32_bf16 v[32:35], v[72:75], v[96:99], v[32:35]
	global_load_lds_dwordx4 v248, s[8:9]
	s_add_u32 m0, s12, 0x400
	v_mfma_f32_16x16x32_bf16 v[36:39], v[72:75], v[100:103], v[36:39]
	global_load_lds_dwordx4 v249, s[8:9]
	s_add_u32 m0, s12, 0x800
	v_mfma_f32_16x16x32_bf16 v[40:43], v[72:75], v[104:107], v[40:43]
	global_load_lds_dwordx4 v250, s[8:9]
	s_add_u32 m0, s12, 0xc00
	v_mfma_f32_16x16x32_bf16 v[44:47], v[72:75], v[108:111], v[44:47]
	global_load_lds_dwordx4 v251, s[8:9]
	s_add_u32 m0, s12, 0x8000
	v_mfma_f32_16x16x32_bf16 v[48:51], v[76:79], v[96:99], v[48:51]
	global_load_lds_dwordx4 v248, s[10:11] sc1
	s_add_u32 m0, s12, 0x8400
	v_mfma_f32_16x16x32_bf16 v[52:55], v[76:79], v[100:103], v[52:55]
	global_load_lds_dwordx4 v249, s[10:11] sc1
	s_add_u32 m0, s12, 0x8800
	v_mfma_f32_16x16x32_bf16 v[56:59], v[76:79], v[104:107], v[56:59]
	global_load_lds_dwordx4 v250, s[10:11] sc1
	s_add_u32 m0, s12, 0x8c00
	v_mfma_f32_16x16x32_bf16 v[60:63], v[76:79], v[108:111], v[60:63]
	global_load_lds_dwordx4 v251, s[10:11] sc1
	s_add_u32 s8, s8, 0x80
	s_addc_u32 s9, s9, 0
	s_add_u32 s10, s10, 0x80
	s_addc_u32 s11, s11, 0
	s_waitcnt vmcnt(8)
	s_barrier
	ds_read_b128 v[64:67], v252 offset:16384
	ds_read_b128 v[96:99], v254 offset:49152
	ds_read_b128 v[100:103], v254 offset:51200
	ds_read_b128 v[104:107], v254 offset:53248
	ds_read_b128 v[108:111], v254 offset:55296
	ds_read_b128 v[68:71], v252 offset:18432
	ds_read_b128 v[72:75], v252 offset:20480
	ds_read_b128 v[76:79], v252 offset:22528
	v_mfma_f32_16x16x32_bf16 v[0:3], v[80:83], v[112:115], v[0:3]
	v_mfma_f32_16x16x32_bf16 v[4:7], v[80:83], v[116:119], v[4:7]
	v_mfma_f32_16x16x32_bf16 v[8:11], v[80:83], v[120:123], v[8:11]
	v_mfma_f32_16x16x32_bf16 v[12:15], v[80:83], v[124:127], v[12:15]
	v_mfma_f32_16x16x32_bf16 v[16:19], v[84:87], v[112:115], v[16:19]
	v_mfma_f32_16x16x32_bf16 v[20:23], v[84:87], v[116:119], v[20:23]
	v_mfma_f32_16x16x32_bf16 v[24:27], v[84:87], v[120:123], v[24:27]
	v_mfma_f32_16x16x32_bf16 v[28:31], v[84:87], v[124:127], v[28:31]
	v_mfma_f32_16x16x32_bf16 v[32:35], v[88:91], v[112:115], v[32:35]
	v_mfma_f32_16x16x32_bf16 v[36:39], v[88:91], v[116:119], v[36:39]
	v_mfma_f32_16x16x32_bf16 v[40:43], v[88:91], v[120:123], v[40:43]
	v_mfma_f32_16x16x32_bf16 v[44:47], v[88:91], v[124:127], v[44:47]
	v_mfma_f32_16x16x32_bf16 v[48:51], v[92:95], v[112:115], v[48:51]
	v_mfma_f32_16x16x32_bf16 v[52:55], v[92:95], v[116:119], v[52:55]
	v_mfma_f32_16x16x32_bf16 v[56:59], v[92:95], v[120:123], v[56:59]
	v_mfma_f32_16x16x32_bf16 v[60:63], v[92:95], v[124:127], v[60:63]
	ds_read_b128 v[80:83], v253 offset:16384
	ds_read_b128 v[112:115], v255 offset:49152
	ds_read_b128 v[116:119], v255 offset:51200
	ds_read_b128 v[120:123], v255 offset:53248
	ds_read_b128 v[124:127], v255 offset:55296
	ds_read_b128 v[84:87], v253 offset:18432
	ds_read_b128 v[88:91], v253 offset:20480
	ds_read_b128 v[92:95], v253 offset:22528
	s_waitcnt lgkmcnt(14)
	v_mfma_f32_16x16x32_bf16 v[0:3], v[64:67], v[96:99], v[0:3]
	s_waitcnt lgkmcnt(13)
	v_mfma_f32_16x16x32_bf16 v[4:7], v[64:67], v[100:103], v[4:7]
	s_waitcnt lgkmcnt(12)
	v_mfma_f32_16x16x32_bf16 v[8:11], v[64:67], v[104:107], v[8:11]
	s_waitcnt lgkmcnt(11)
	v_mfma_f32_16x16x32_bf16 v[12:15], v[64:67], v[108:111], v[12:15]
	s_waitcnt lgkmcnt(10)
	v_mfma_f32_16x16x32_bf16 v[16:19], v[68:71], v[96:99], v[16:19]
	v_mfma_f32_16x16x32_bf16 v[20:23], v[68:71], v[100:103], v[20:23]
	v_mfma_f32_16x16x32_bf16 v[24:27], v[68:71], v[104:107], v[24:27]
	v_mfma_f32_16x16x32_bf16 v[28:31], v[68:71], v[108:111], v[28:31]
	s_waitcnt lgkmcnt(0)
	s_barrier
	s_add_u32 m0, s12, 0x4000
	v_mfma_f32_16x16x32_bf16 v[32:35], v[72:75], v[96:99], v[32:35]
	global_load_lds_dwordx4 v248, s[8:9]
	s_add_u32 m0, s12, 0x4400
	v_mfma_f32_16x16x32_bf16 v[36:39], v[72:75], v[100:103], v[36:39]
	global_load_lds_dwordx4 v249, s[8:9]
	s_add_u32 m0, s12, 0x4800
	v_mfma_f32_16x16x32_bf16 v[40:43], v[72:75], v[104:107], v[40:43]
	global_load_lds_dwordx4 v250, s[8:9]
	s_add_u32 m0, s12, 0x4c00
	v_mfma_f32_16x16x32_bf16 v[44:47], v[72:75], v[108:111], v[44:47]
	global_load_lds_dwordx4 v251, s[8:9]
	s_add_u32 m0, s12, 0xc000
	v_mfma_f32_16x16x32_bf16 v[48:51], v[76:79], v[96:99], v[48:51]
	global_load_lds_dwordx4 v248, s[10:11] sc1
	s_add_u32 m0, s12, 0xc400
	v_mfma_f32_16x16x32_bf16 v[52:55], v[76:79], v[100:103], v[52:55]
	global_load_lds_dwordx4 v249, s[10:11] sc1
	s_add_u32 m0, s12, 0xc800
	v_mfma_f32_16x16x32_bf16 v[56:59], v[76:79], v[104:107], v[56:59]
	global_load_lds_dwordx4 v250, s[10:11] sc1
	s_add_u32 m0, s12, 0xcc00
	v_mfma_f32_16x16x32_bf16 v[60:63], v[76:79], v[108:111], v[60:63]
	global_load_lds_dwordx4 v251, s[10:11] sc1
	s_add_u32 s8, s8, 0x80
	s_addc_u32 s9, s9, 0
	s_add_u32 s10, s10, 0x80
	s_addc_u32 s11, s11, 0
	s_sub_u32 s13, s13, 1
	s_cmp_lg_u32 s13, 0
	s_cbranch_scc1 .Lr13_loop
	s_waitcnt vmcnt(8)
	s_barrier
	ds_read_b128 v[64:67], v252 offset:0
	ds_read_b128 v[96:99], v254 offset:32768
	ds_read_b128 v[100:103], v254 offset:34816
	ds_read_b128 v[104:107], v254 offset:36864
	ds_read_b128 v[108:111], v254 offset:38912
	ds_read_b128 v[68:71], v252 offset:2048
	ds_read_b128 v[72:75], v252 offset:4096
	ds_read_b128 v[76:79], v252 offset:6144
	v_mfma_f32_16x16x32_bf16 v[0:3], v[80:83], v[112:115], v[0:3]
	v_mfma_f32_16x16x32_bf16 v[4:7], v[80:83], v[116:119], v[4:7]
	v_mfma_f32_16x16x32_bf16 v[8:11], v[80:83], v[120:123], v[8:11]
	v_mfma_f32_16x16x32_bf16 v[12:15], v[80:83], v[124:127], v[12:15]
	v_mfma_f32_16x16x32_bf16 v[16:19], v[84:87], v[112:115], v[16:19]
	v_mfma_f32_16x16x32_bf16 v[20:23], v[84:87], v[116:119], v[20:23]
	v_mfma_f32_16x16x32_bf16 v[24:27], v[84:87], v[120:123], v[24:27]
	v_mfma_f32_16x16x32_bf16 v[28:31], v[84:87], v[124:127], v[28:31]
	v_mfma_f32_16x16x32_bf16 v[32:35], v[88:91], v[112:115], v[32:35]
	v_mfma_f32_16x16x32_bf16 v[36:39], v[88:91], v[116:119], v[36:39]
	v_mfma_f32_16x16x32_bf16 v[40:43], v[88:91], v[120:123], v[40:43]
	v_mfma_f32_16x16x32_bf16 v[44:47], v[88:91], v[124:127], v[44:47]
	v_mfma_f32_16x16x32_bf16 v[48:51], v[92:95], v[112:115], v[48:51]
	v_mfma_f32_16x16x32_bf16 v[52:55], v[92:95], v[116:119], v[52:55]
	v_mfma_f32_16x16x32_bf16 v[56:59], v[92:95], v[120:123], v[56:59]
	v_mfma_f32_16x16x32_bf16 v[60:63], v[92:95], v[124:127], v[60:63]
	ds_read_b128 v[80:83], v253 offset:0
	ds_read_b128 v[112:115], v255 offset:32768
	ds_read_b128 v[116:119], v255 offset:34816
	ds_read_b128 v[120:123], v255 offset:36864
	ds_read_b128 v[124:127], v255 offset:38912
	ds_read_b128 v[84:87], v253 offset:2048
	ds_read_b128 v[88:91], v253 offset:4096
	ds_read_b128 v[92:95], v253 offset:6144
	s_waitcnt lgkmcnt(14)
	v_mfma_f32_16x16x32_bf16 v[0:3], v[64:67], v[96:99], v[0:3]
	s_waitcnt lgkmcnt(13)
	v_mfma_f32_16x16x32_bf16 v[4:7], v[64:67], v[100:103], v[4:7]
	s_waitcnt lgkmcnt(12)
	v_mfma_f32_16x16x32_bf16 v[8:11], v[64:67], v[104:107], v[8:11]
	s_waitcnt lgkmcnt(11)
	v_mfma_f32_16x16x32_bf16 v[12:15], v[64:67], v[108:111], v[12:15]
	s_waitcnt lgkmcnt(10)
	v_mfma_f32_16x16x32_bf16 v[16:19], v[68:71], v[96:99], v[16:19]
	v_mfma_f32_16x16x32_bf16 v[20:23], v[68:71], v[100:103], v[20:23]
	v_mfma_f32_16x16x32_bf16 v[24:27], v[68:71], v[104:107], v[24:27]
	v_mfma_f32_16x16x32_bf16 v[28:31], v[68:71], v[108:111], v[28:31]
	s_waitcnt lgkmcnt(0)
	s_barrier
	v_mfma_f32_16x16x32_bf16 v[32:35], v[72:75], v[96:99], v[32:35]
	v_mfma_f32_16x16x32_bf16 v[36:39], v[72:75], v[100:103], v[36:39]
	v_mfma_f32_16x16x32_bf16 v[40:43], v[72:75], v[104:107], v[40:43]
	v_mfma_f32_16x16x32_bf16 v[44:47], v[72:75], v[108:111], v[44:47]
	v_mfma_f32_16x16x32_bf16 v[48:51], v[76:79], v[96:99], v[48:51]
	v_mfma_f32_16x16x32_bf16 v[52:55], v[76:79], v[100:103], v[52:55]
	v_mfma_f32_16x16x32_bf16 v[56:59], v[76:79], v[104:107], v[56:59]
	v_mfma_f32_16x16x32_bf16 v[60:63], v[76:79], v[108:111], v[60:63]
	s_waitcnt vmcnt(0)
	s_barrier
	ds_read_b128 v[64:67], v252 offset:16384
	ds_read_b128 v[96:99], v254 offset:49152
	ds_read_b128 v[100:103], v254 offset:51200
	ds_read_b128 v[104:107], v254 offset:53248
	ds_read_b128 v[108:111], v254 offset:55296
	ds_read_b128 v[68:71], v252 offset:18432
	ds_read_b128 v[72:75], v252 offset:20480
	ds_read_b128 v[76:79], v252 offset:22528
	v_mfma_f32_16x16x32_bf16 v[0:3], v[80:83], v[112:115], v[0:3]
	v_mfma_f32_16x16x32_bf16 v[4:7], v[80:83], v[116:119], v[4:7]
	v_mfma_f32_16x16x32_bf16 v[8:11], v[80:83], v[120:123], v[8:11]
	v_mfma_f32_16x16x32_bf16 v[12:15], v[80:83], v[124:127], v[12:15]
	v_mfma_f32_16x16x32_bf16 v[16:19], v[84:87], v[112:115], v[16:19]
	v_mfma_f32_16x16x32_bf16 v[20:23], v[84:87], v[116:119], v[20:23]
	v_mfma_f32_16x16x32_bf16 v[24:27], v[84:87], v[120:123], v[24:27]
	v_mfma_f32_16x16x32_bf16 v[28:31], v[84:87], v[124:127], v[28:31]
	v_mfma_f32_16x16x32_bf16 v[32:35], v[88:91], v[112:115], v[32:35]
	v_mfma_f32_16x16x32_bf16 v[36:39], v[88:91], v[116:119], v[36:39]
	v_mfma_f32_16x16x32_bf16 v[40:43], v[88:91], v[120:123], v[40:43]
	v_mfma_f32_16x16x32_bf16 v[44:47], v[88:91], v[124:127], v[44:47]
	v_mfma_f32_16x16x32_bf16 v[48:51], v[92:95], v[112:115], v[48:51]
	v_mfma_f32_16x16x32_bf16 v[52:55], v[92:95], v[116:119], v[52:55]
	v_mfma_f32_16x16x32_bf16 v[56:59], v[92:95], v[120:123], v[56:59]
	v_mfma_f32_16x16x32_bf16 v[60:63], v[92:95], v[124:127], v[60:63]
	ds_read_b128 v[80:83], v253 offset:16384
	ds_read_b128 v[112:115], v255 offset:49152
	ds_read_b128 v[116:119], v255 offset:51200
	ds_read_b128 v[120:123], v255 offset:53248
	ds_read_b128 v[124:127], v255 offset:55296
	ds_read_b128 v[84:87], v253 offset:18432
	ds_read_b128 v[88:91], v253 offset:20480
	ds_read_b128 v[92:95], v253 offset:22528
	s_waitcnt lgkmcnt(14)
	v_mfma_f32_16x16x32_bf16 v[0:3], v[64:67], v[96:99], v[0:3]
	s_waitcnt lgkmcnt(13)
	v_mfma_f32_16x16x32_bf16 v[4:7], v[64:67], v[100:103], v[4:7]
	s_waitcnt lgkmcnt(12)
	v_mfma_f32_16x16x32_bf16 v[8:11], v[64:67], v[104:107], v[8:11]
	s_waitcnt lgkmcnt(11)
	v_mfma_f32_16x16x32_bf16 v[12:15], v[64:67], v[108:111], v[12:15]
	s_waitcnt lgkmcnt(10)
	v_mfma_f32_16x16x32_bf16 v[16:19], v[68:71], v[96:99], v[16:19]
	v_mfma_f32_16x16x32_bf16 v[20:23], v[68:71], v[100:103], v[20:23]
	v_mfma_f32_16x16x32_bf16 v[24:27], v[68:71], v[104:107], v[24:27]
	v_mfma_f32_16x16x32_bf16 v[28:31], v[68:71], v[108:111], v[28:31]
	s_waitcnt lgkmcnt(0)
	s_barrier
	v_mfma_f32_16x16x32_bf16 v[32:35], v[72:75], v[96:99], v[32:35]
	v_mfma_f32_16x16x32_bf16 v[36:39], v[72:75], v[100:103], v[36:39]
	v_mfma_f32_16x16x32_bf16 v[40:43], v[72:75], v[104:107], v[40:43]
	v_mfma_f32_16x16x32_bf16 v[44:47], v[72:75], v[108:111], v[44:47]
	v_mfma_f32_16x16x32_bf16 v[48:51], v[76:79], v[96:99], v[48:51]
	v_mfma_f32_16x16x32_bf16 v[52:55], v[76:79], v[100:103], v[52:55]
	v_mfma_f32_16x16x32_bf16 v[56:59], v[76:79], v[104:107], v[56:59]
	v_mfma_f32_16x16x32_bf16 v[60:63], v[76:79], v[108:111], v[60:63]
	v_mfma_f32_16x16x32_bf16 v[0:3], v[80:83], v[112:115], v[0:3]
	v_mfma_f32_16x16x32_bf16 v[4:7], v[80:83], v[116:119], v[4:7]
	v_mfma_f32_16x16x32_bf16 v[8:11], v[80:83], v[120:123], v[8:11]
	v_mfma_f32_16x16x32_bf16 v[12:15], v[80:83], v[124:127], v[12:15]
	v_mfma_f32_16x16x32_bf16 v[16:19], v[84:87], v[112:115], v[16:19]
	v_mfma_f32_16x16x32_bf16 v[20:23], v[84:87], v[116:119], v[20:23]
	v_mfma_f32_16x16x32_bf16 v[24:27], v[84:87], v[120:123], v[24:27]
	v_mfma_f32_16x16x32_bf16 v[28:31], v[84:87], v[124:127], v[28:31]
	v_mfma_f32_16x16x32_bf16 v[32:35], v[88:91], v[112:115], v[32:35]
	v_mfma_f32_16x16x32_bf16 v[36:39], v[88:91], v[116:119], v[36:39]
	v_mfma_f32_16x16x32_bf16 v[40:43], v[88:91], v[120:123], v[40:43]
	v_mfma_f32_16x16x32_bf16 v[44:47], v[88:91], v[124:127], v[44:47]
	v_mfma_f32_16x16x32_bf16 v[48:51], v[92:95], v[112:115], v[48:51]
	v_mfma_f32_16x16x32_bf16 v[52:55], v[92:95], v[116:119], v[52:55]
	v_mfma_f32_16x16x32_bf16 v[56:59], v[92:95], v[120:123], v[56:59]
	v_mfma_f32_16x16x32_bf16 v[60:63], v[92:95], v[124:127], v[60:63]
	s_nop 7
	s_nop 1
	s_mov_b64 s[18:19], s[20:21]
	v_add_f32_e32 v0, v0, v205
	v_add_f32_e32 v4, v4, v206
	v_add_f32_e32 v8, v8, v207
	v_add_f32_e32 v12, v12, v208
	v_fma_f32 v129, v201, v0, v129
	v_fma_f32 v130, v202, v4, v130
	v_fma_f32 v131, v203, v8, v131
	v_fma_f32 v132, v204, v12, v132
	global_store_dword v246, v129, s[18:19] offset:0 sc0 sc1
	global_store_dword v246, v130, s[18:19] offset:64 sc0 sc1
	global_store_dword v246, v131, s[18:19] offset:128 sc0 sc1
	global_store_dword v246, v132, s[18:19] offset:192 sc0 sc1
	s_add_u32 s18, s18, 0x1000
	s_addc_u32 s19, s19, 0
	v_add_f32_e32 v1, v1, v205
	v_add_f32_e32 v5, v5, v206
	v_add_f32_e32 v9, v9, v207
	v_add_f32_e32 v13, v13, v208
	v_fma_f32 v133, v201, v1, v133
	v_fma_f32 v134, v202, v5, v134
	v_fma_f32 v135, v203, v9, v135
	v_fma_f32 v136, v204, v13, v136
	global_store_dword v246, v133, s[18:19] offset:0 sc0 sc1
	global_store_dword v246, v134, s[18:19] offset:64 sc0 sc1
	global_store_dword v246, v135, s[18:19] offset:128 sc0 sc1
	global_store_dword v246, v136, s[18:19] offset:192 sc0 sc1
	s_add_u32 s18, s18, 0x1000
	s_addc_u32 s19, s19, 0
	v_add_f32_e32 v2, v2, v205
	v_add_f32_e32 v6, v6, v206
	v_add_f32_e32 v10, v10, v207
	v_add_f32_e32 v14, v14, v208
	v_fma_f32 v137, v201, v2, v137
	v_fma_f32 v138, v202, v6, v138
	v_fma_f32 v139, v203, v10, v139
	v_fma_f32 v140, v204, v14, v140
	global_store_dword v246, v137, s[18:19] offset:0 sc0 sc1
	global_store_dword v246, v138, s[18:19] offset:64 sc0 sc1
	global_store_dword v246, v139, s[18:19] offset:128 sc0 sc1
	global_store_dword v246, v140, s[18:19] offset:192 sc0 sc1
	s_add_u32 s18, s18, 0x1000
	s_addc_u32 s19, s19, 0
	v_add_f32_e32 v3, v3, v205
	v_add_f32_e32 v7, v7, v206
	v_add_f32_e32 v11, v11, v207
	v_add_f32_e32 v15, v15, v208
	v_fma_f32 v141, v201, v3, v141
	v_fma_f32 v142, v202, v7, v142
	v_fma_f32 v143, v203, v11, v143
	v_fma_f32 v144, v204, v15, v144
	global_store_dword v246, v141, s[18:19] offset:0 sc0 sc1
	global_store_dword v246, v142, s[18:19] offset:64 sc0 sc1
	global_store_dword v246, v143, s[18:19] offset:128 sc0 sc1
	global_store_dword v246, v144, s[18:19] offset:192 sc0 sc1
	s_add_u32 s18, s18, 0xd000
	s_addc_u32 s19, s19, 0
	v_add_f32_e32 v16, v16, v205
	v_add_f32_e32 v20, v20, v206
	v_add_f32_e32 v24, v24, v207
	v_add_f32_e32 v28, v28, v208
	v_fma_f32 v145, v201, v16, v145
	v_fma_f32 v146, v202, v20, v146
	v_fma_f32 v147, v203, v24, v147
	v_fma_f32 v148, v204, v28, v148
	global_store_dword v246, v145, s[18:19] offset:0 sc0 sc1
	global_store_dword v246, v146, s[18:19] offset:64 sc0 sc1
	global_store_dword v246, v147, s[18:19] offset:128 sc0 sc1
	global_store_dword v246, v148, s[18:19] offset:192 sc0 sc1
	s_add_u32 s18, s18, 0x1000
	s_addc_u32 s19, s19, 0
	v_add_f32_e32 v17, v17, v205
	v_add_f32_e32 v21, v21, v206
	v_add_f32_e32 v25, v25, v207
	v_add_f32_e32 v29, v29, v208
	v_fma_f32 v149, v201, v17, v149
	v_fma_f32 v150, v202, v21, v150
	v_fma_f32 v151, v203, v25, v151
	v_fma_f32 v152, v204, v29, v152
	global_store_dword v246, v149, s[18:19] offset:0 sc0 sc1
	global_store_dword v246, v150, s[18:19] offset:64 sc0 sc1
	global_store_dword v246, v151, s[18:19] offset:128 sc0 sc1
	global_store_dword v246, v152, s[18:19] offset:192 sc0 sc1
	s_add_u32 s18, s18, 0x1000
	s_addc_u32 s19, s19, 0
	v_add_f32_e32 v18, v18, v205
	v_add_f32_e32 v22, v22, v206
	v_add_f32_e32 v26, v26, v207
	v_add_f32_e32 v30, v30, v208
	v_fma_f32 v153, v201, v18, v153
	v_fma_f32 v154, v202, v22, v154
	v_fma_f32 v155, v203, v26, v155
	v_fma_f32 v156, v204, v30, v156
	global_store_dword v246, v153, s[18:19] offset:0 sc0 sc1
	global_store_dword v246, v154, s[18:19] offset:64 sc0 sc1
	global_store_dword v246, v155, s[18:19] offset:128 sc0 sc1
	global_store_dword v246, v156, s[18:19] offset:192 sc0 sc1
	s_add_u32 s18, s18, 0x1000
	s_addc_u32 s19, s19, 0
	v_add_f32_e32 v19, v19, v205
	v_add_f32_e32 v23, v23, v206
	v_add_f32_e32 v27, v27, v207
	v_add_f32_e32 v31, v31, v208
	v_fma_f32 v157, v201, v19, v157
	v_fma_f32 v158, v202, v23, v158
	v_fma_f32 v159, v203, v27, v159
	v_fma_f32 v160, v204, v31, v160
	global_store_dword v246, v157, s[18:19] offset:0 sc0 sc1
	global_store_dword v246, v158, s[18:19] offset:64 sc0 sc1
	global_store_dword v246, v159, s[18:19] offset:128 sc0 sc1
	global_store_dword v246, v160, s[18:19] offset:192 sc0 sc1
	s_add_u32 s18, s18, 0xd000
	s_addc_u32 s19, s19, 0
	v_add_f32_e32 v32, v32, v205
	v_add_f32_e32 v36, v36, v206
	v_add_f32_e32 v40, v40, v207
	v_add_f32_e32 v44, v44, v208
	v_fma_f32 v161, v201, v32, v161
	v_fma_f32 v170, v202, v36, v170
	v_fma_f32 v171, v203, v40, v171
	v_fma_f32 v172, v204, v44, v172
	global_store_dword v246, v161, s[18:19] offset:0 sc0 sc1
	global_store_dword v246, v170, s[18:19] offset:64 sc0 sc1
	global_store_dword v246, v171, s[18:19] offset:128 sc0 sc1
	global_store_dword v246, v172, s[18:19] offset:192 sc0 sc1
	s_add_u32 s18, s18, 0x1000
	s_addc_u32 s19, s19, 0
	v_add_f32_e32 v33, v33, v205
	v_add_f32_e32 v37, v37, v206
	v_add_f32_e32 v41, v41, v207
	v_add_f32_e32 v45, v45, v208
	v_fma_f32 v173, v201, v33, v173
	v_fma_f32 v174, v202, v37, v174
	v_fma_f32 v175, v203, v41, v175
	v_fma_f32 v176, v204, v45, v176
	global_store_dword v246, v173, s[18:19] offset:0 sc0 sc1
	global_store_dword v246, v174, s[18:19] offset:64 sc0 sc1
	global_store_dword v246, v175, s[18:19] offset:128 sc0 sc1
	global_store_dword v246, v176, s[18:19] offset:192 sc0 sc1
	s_add_u32 s18, s18, 0x1000
	s_addc_u32 s19, s19, 0
	v_add_f32_e32 v34, v34, v205
	v_add_f32_e32 v38, v38, v206
	v_add_f32_e32 v42, v42, v207
	v_add_f32_e32 v46, v46, v208
	v_fma_f32 v177, v201, v34, v177
	v_fma_f32 v178, v202, v38, v178
	v_fma_f32 v179, v203, v42, v179
	v_fma_f32 v180, v204, v46, v180
	global_store_dword v246, v177, s[18:19] offset:0 sc0 sc1
	global_store_dword v246, v178, s[18:19] offset:64 sc0 sc1
	global_store_dword v246, v179, s[18:19] offset:128 sc0 sc1
	global_store_dword v246, v180, s[18:19] offset:192 sc0 sc1
	s_add_u32 s18, s18, 0x1000
	s_addc_u32 s19, s19, 0
	v_add_f32_e32 v35, v35, v205
	v_add_f32_e32 v39, v39, v206
	v_add_f32_e32 v43, v43, v207
	v_add_f32_e32 v47, v47, v208
	v_fma_f32 v181, v201, v35, v181
	v_fma_f32 v182, v202, v39, v182
	v_fma_f32 v183, v203, v43, v183
	v_fma_f32 v184, v204, v47, v184
	global_store_dword v246, v181, s[18:19] offset:0 sc0 sc1
	global_store_dword v246, v182, s[18:19] offset:64 sc0 sc1
	global_store_dword v246, v183, s[18:19] offset:128 sc0 sc1
	global_store_dword v246, v184, s[18:19] offset:192 sc0 sc1
	s_add_u32 s18, s18, 0xd000
	s_addc_u32 s19, s19, 0
	v_add_f32_e32 v48, v48, v205
	v_add_f32_e32 v52, v52, v206
	v_add_f32_e32 v56, v56, v207
	v_add_f32_e32 v60, v60, v208
	v_fma_f32 v185, v201, v48, v185
	v_fma_f32 v186, v202, v52, v186
	v_fma_f32 v187, v203, v56, v187
	v_fma_f32 v188, v204, v60, v188
	global_store_dword v246, v185, s[18:19] offset:0 sc0 sc1
	global_store_dword v246, v186, s[18:19] offset:64 sc0 sc1
	global_store_dword v246, v187, s[18:19] offset:128 sc0 sc1
	global_store_dword v246, v188, s[18:19] offset:192 sc0 sc1
	s_add_u32 s18, s18, 0x1000
	s_addc_u32 s19, s19, 0
	v_add_f32_e32 v49, v49, v205
	v_add_f32_e32 v53, v53, v206
	v_add_f32_e32 v57, v57, v207
	v_add_f32_e32 v61, v61, v208
	v_fma_f32 v189, v201, v49, v189
	v_fma_f32 v190, v202, v53, v190
	v_fma_f32 v191, v203, v57, v191
	v_fma_f32 v192, v204, v61, v192
	global_store_dword v246, v189, s[18:19] offset:0 sc0 sc1
	global_store_dword v246, v190, s[18:19] offset:64 sc0 sc1
	global_store_dword v246, v191, s[18:19] offset:128 sc0 sc1
	global_store_dword v246, v192, s[18:19] offset:192 sc0 sc1
	s_add_u32 s18, s18, 0x1000
	s_addc_u32 s19, s19, 0
	v_add_f32_e32 v50, v50, v205
	v_add_f32_e32 v54, v54, v206
	v_add_f32_e32 v58, v58, v207
	v_add_f32_e32 v62, v62, v208
	v_fma_f32 v193, v201, v50, v193
	v_fma_f32 v194, v202, v54, v194
	v_fma_f32 v195, v203, v58, v195
	v_fma_f32 v196, v204, v62, v196
	global_store_dword v246, v193, s[18:19] offset:0 sc0 sc1
	global_store_dword v246, v194, s[18:19] offset:64 sc0 sc1
	global_store_dword v246, v195, s[18:19] offset:128 sc0 sc1
	global_store_dword v246, v196, s[18:19] offset:192 sc0 sc1
	s_add_u32 s18, s18, 0x1000
	s_addc_u32 s19, s19, 0
	v_add_f32_e32 v51, v51, v205
	v_add_f32_e32 v55, v55, v206
	v_add_f32_e32 v59, v59, v207
	v_add_f32_e32 v63, v63, v208
	v_fma_f32 v197, v201, v51, v197
	v_fma_f32 v198, v202, v55, v198
	v_fma_f32 v199, v203, v59, v199
	v_fma_f32 v200, v204, v63, v200
	global_store_dword v246, v197, s[18:19] offset:0 sc0 sc1
	global_store_dword v246, v198, s[18:19] offset:64 sc0 sc1
	global_store_dword v246, v199, s[18:19] offset:128 sc0 sc1
	global_store_dword v246, v200, s[18:19] offset:192 sc0 sc1
	s_add_u32 s15, s15, s16
	s_branch .Lr13_tile
